# first K iteration of each GEMM tile peeled: its first MFMA per accumulator takes C=0, per-tile accumulator zeroing removed (P1,P4,P5,P6,P7)
# speedup vs baseline: 1.0103x; 1.0060x over previous
.LBB0_161:
	s_add_u32 s86, s69, s6
	s_addc_u32 s87, s70, s7
	s_add_u32 s88, s71, s8
	s_addc_u32 s89, s72, s9
	s_ashr_i32 s23, s22, 31
	s_lshl_b64 s[6:7], s[22:23], 19
	s_add_u32 s24, s34, s6
	s_addc_u32 s25, s35, s7
	s_and_b64 s[8:9], s[0:1], exec
	s_cselect_b32 s23, s25, s43
	s_cselect_b32 s90, s24, s42
	s_ashr_i32 s21, s20, 31
	s_lshl_b64 s[8:9], s[20:21], 19
	s_add_u32 s26, s17, s8
	s_addc_u32 s27, s19, s9
	s_and_b64 s[48:49], s[0:1], exec
	s_cselect_b32 s21, s27, s39
	s_cselect_b32 s91, s26, s38
	s_add_u32 s48, s90, 0x80
	s_addc_u32 s49, s23, 0
	s_add_u32 s54, s91, 0x80
	s_addc_u32 s55, s21, 0
	v_lshl_add_u64 v[128:129], s[42:43], 0, v[150:151]
	v_lshl_add_u64 v[130:131], s[42:43], 0, v[152:153]
	s_mov_b32 s92, 0
	s_mov_b64 s[56:57], 0
	s_cmpk_eq_i32 s56, 0x700
	s_cselect_b64 s[62:63], -1, 0
	s_add_u32 s64, s42, s56
	s_addc_u32 s65, s43, s57
	s_add_u32 s94, s38, s56
	s_addc_u32 s93, s39, s57
	s_add_u32 s58, s64, 0x180
	s_addc_u32 s59, s65, 0
	s_add_u32 s60, s94, 0x180
	s_addc_u32 s61, s93, 0
	s_cmpk_eq_i32 s56, 0x700
	s_cselect_b32 s58, s48, s58
	s_cselect_b32 s59, s49, s59
	s_cselect_b32 s60, s54, s60
	s_cselect_b32 s61, s55, s61
	v_add_u32_e32 v144, s82, v171
	ds_read_b128 v[132:135], v144
	ds_read_b128 v[158:161], v144 offset:1024
	ds_read_b128 v[162:165], v144 offset:2048
	ds_read_b128 v[166:169], v144 offset:3072
	v_add_u32_e32 v144, s83, v171
	ds_read_b128 v[184:187], v144
	ds_read_b128 v[188:191], v144 offset:1024
	ds_read_b128 v[192:195], v144 offset:2048
	ds_read_b128 v[196:199], v144 offset:3072
	s_add_u32 s10, s64, 0x100
	s_addc_u32 s95, s65, 0
	s_and_b64 s[64:65], exec, s[62:63]
	s_cselect_b32 s65, s23, s95
	s_cselect_b32 s64, s90, s10
	s_add_u32 s10, s94, 0x100
	s_addc_u32 s93, s93, 0
	s_and_b64 s[62:63], exec, s[62:63]
	s_cselect_b32 s63, s21, s93
	s_cselect_b32 s62, s91, s10
	v_lshl_add_u64 v[232:233], v[128:129], 0, s[56:57]
	s_add_i32 m0, s29, 0xc000
	ds_read_b128 v[200:203], v181
	ds_read_b128 v[204:207], v181 offset:1024
	ds_read_b128 v[208:211], v181 offset:2048
	ds_read_b128 v[212:215], v181 offset:3072
	ds_read_b128 v[216:219], v181 offset:4096
	ds_read_b128 v[220:223], v181 offset:5120
	ds_read_b128 v[224:227], v181 offset:6144
	ds_read_b128 v[228:231], v181 offset:7168
	global_load_lds_dwordx4 v[232:233], off
	v_lshl_add_u64 v[232:233], v[130:131], 0, s[56:57]
	s_add_i32 m0, s29, 0xe000
	s_nop 0
	global_load_lds_dwordx4 v[232:233], off
	s_waitcnt vmcnt(8)
	s_waitcnt lgkmcnt(0)
	s_barrier
	s_setprio 1
	s_waitcnt lgkmcnt(0)
	v_mfma_f32_16x16x32_bf16 v[124:127], v[132:135], v[200:203], 0
	v_mfma_f32_16x16x32_bf16 v[120:123], v[162:165], v[200:203], 0
	v_mfma_f32_16x16x32_bf16 v[108:111], v[132:135], v[208:211], 0
	v_mfma_f32_16x16x32_bf16 v[104:107], v[162:165], v[208:211], 0
	v_mfma_f32_16x16x32_bf16 v[92:95], v[132:135], v[216:219], 0
	v_mfma_f32_16x16x32_bf16 v[88:91], v[162:165], v[216:219], 0
	v_mfma_f32_16x16x32_bf16 v[76:79], v[132:135], v[224:227], 0
	v_mfma_f32_16x16x32_bf16 v[72:75], v[162:165], v[224:227], 0
	v_mfma_f32_16x16x32_bf16 v[124:127], v[158:161], v[204:207], v[124:127]
	v_mfma_f32_16x16x32_bf16 v[120:123], v[166:169], v[204:207], v[120:123]
	v_mfma_f32_16x16x32_bf16 v[108:111], v[158:161], v[212:215], v[108:111]
	v_mfma_f32_16x16x32_bf16 v[104:107], v[166:169], v[212:215], v[104:107]
	v_mfma_f32_16x16x32_bf16 v[92:95], v[158:161], v[220:223], v[92:95]
	v_mfma_f32_16x16x32_bf16 v[88:91], v[166:169], v[220:223], v[88:91]
	v_mfma_f32_16x16x32_bf16 v[76:79], v[158:161], v[228:231], v[76:79]
	v_mfma_f32_16x16x32_bf16 v[72:75], v[166:169], v[228:231], v[72:75]
	s_setprio 0
	s_setprio 1
	v_mfma_f32_16x16x32_bf16 v[116:119], v[184:187], v[200:203], 0
	v_mfma_f32_16x16x32_bf16 v[112:115], v[192:195], v[200:203], 0
	v_mfma_f32_16x16x32_bf16 v[100:103], v[184:187], v[208:211], 0
	v_mfma_f32_16x16x32_bf16 v[96:99], v[192:195], v[208:211], 0
	v_mfma_f32_16x16x32_bf16 v[84:87], v[184:187], v[216:219], 0
	v_mfma_f32_16x16x32_bf16 v[80:83], v[192:195], v[216:219], 0
	v_mfma_f32_16x16x32_bf16 v[68:71], v[184:187], v[224:227], 0
	v_mfma_f32_16x16x32_bf16 v[64:67], v[192:195], v[224:227], 0
	v_mfma_f32_16x16x32_bf16 v[116:119], v[188:191], v[204:207], v[116:119]
	v_mfma_f32_16x16x32_bf16 v[112:115], v[196:199], v[204:207], v[112:115]
	v_mfma_f32_16x16x32_bf16 v[100:103], v[188:191], v[212:215], v[100:103]
	v_mfma_f32_16x16x32_bf16 v[96:99], v[196:199], v[212:215], v[96:99]
	v_mfma_f32_16x16x32_bf16 v[84:87], v[188:191], v[220:223], v[84:87]
	v_mfma_f32_16x16x32_bf16 v[80:83], v[196:199], v[220:223], v[80:83]
	v_mfma_f32_16x16x32_bf16 v[68:71], v[188:191], v[228:231], v[68:71]
	v_mfma_f32_16x16x32_bf16 v[64:67], v[196:199], v[228:231], v[64:67]
	s_setprio 0
	s_barrier
	s_add_i32 s10, s82, s66
	s_mov_b32 m0, s10
	ds_read_b128 v[200:203], v181 offset:16384
	ds_read_b128 v[204:207], v181 offset:17408
	ds_read_b128 v[208:211], v181 offset:18432
	ds_read_b128 v[212:215], v181 offset:19456
	ds_read_b128 v[216:219], v181 offset:20480
	ds_read_b128 v[220:223], v181 offset:21504
	ds_read_b128 v[224:227], v181 offset:22528
	ds_read_b128 v[228:231], v181 offset:23552
	global_load_lds_dwordx4 v138, s[62:63]
	s_add_i32 m0, s10, 0x2000
	s_nop 0
	global_load_lds_dwordx4 v142, s[62:63]
	s_add_u32 s62, s62, 0x40000
	s_addc_u32 s63, s63, 0
	s_add_i32 s10, s83, s66
	s_mov_b32 m0, s10
	s_nop 0
	global_load_lds_dwordx4 v138, s[62:63]
	s_add_i32 m0, s10, 0x2000
	s_nop 0
	global_load_lds_dwordx4 v142, s[62:63]
	s_mov_b32 m0, s29
	s_nop 0
	global_load_lds_dwordx4 v136, s[64:65]
	s_mov_b32 m0, s31
	s_nop 0
	global_load_lds_dwordx4 v140, s[64:65]
	s_waitcnt vmcnt(8)
	s_waitcnt lgkmcnt(0)
	s_barrier
	s_setprio 1
	s_waitcnt lgkmcnt(0)
	v_mfma_f32_16x16x32_bf16 v[60:63], v[132:135], v[200:203], 0
	v_mfma_f32_16x16x32_bf16 v[56:59], v[162:165], v[200:203], 0
	v_mfma_f32_16x16x32_bf16 v[44:47], v[132:135], v[208:211], 0
	v_mfma_f32_16x16x32_bf16 v[40:43], v[162:165], v[208:211], 0
	v_mfma_f32_16x16x32_bf16 v[28:31], v[132:135], v[216:219], 0
	v_mfma_f32_16x16x32_bf16 v[24:27], v[162:165], v[216:219], 0
	v_mfma_f32_16x16x32_bf16 v[12:15], v[132:135], v[224:227], 0
	v_mfma_f32_16x16x32_bf16 v[8:11], v[162:165], v[224:227], 0
	v_mfma_f32_16x16x32_bf16 v[60:63], v[158:161], v[204:207], v[60:63]
	v_mfma_f32_16x16x32_bf16 v[56:59], v[166:169], v[204:207], v[56:59]
	v_mfma_f32_16x16x32_bf16 v[44:47], v[158:161], v[212:215], v[44:47]
	v_mfma_f32_16x16x32_bf16 v[40:43], v[166:169], v[212:215], v[40:43]
	v_mfma_f32_16x16x32_bf16 v[28:31], v[158:161], v[220:223], v[28:31]
	v_mfma_f32_16x16x32_bf16 v[24:27], v[166:169], v[220:223], v[24:27]
	v_mfma_f32_16x16x32_bf16 v[12:15], v[158:161], v[228:231], v[12:15]
	v_mfma_f32_16x16x32_bf16 v[8:11], v[166:169], v[228:231], v[8:11]
	s_setprio 0
	s_setprio 1
	v_mfma_f32_16x16x32_bf16 v[52:55], v[184:187], v[200:203], 0
	v_mfma_f32_16x16x32_bf16 v[48:51], v[192:195], v[200:203], 0
	v_mfma_f32_16x16x32_bf16 v[36:39], v[184:187], v[208:211], 0
	v_mfma_f32_16x16x32_bf16 v[32:35], v[192:195], v[208:211], 0
	v_mfma_f32_16x16x32_bf16 v[20:23], v[184:187], v[216:219], 0
	v_mfma_f32_16x16x32_bf16 v[16:19], v[192:195], v[216:219], 0
	v_mfma_f32_16x16x32_bf16 v[4:7], v[184:187], v[224:227], 0
	v_mfma_f32_16x16x32_bf16 v[0:3], v[192:195], v[224:227], 0
	v_mfma_f32_16x16x32_bf16 v[52:55], v[188:191], v[204:207], v[52:55]
	v_mfma_f32_16x16x32_bf16 v[48:51], v[196:199], v[204:207], v[48:51]
	v_mfma_f32_16x16x32_bf16 v[36:39], v[188:191], v[212:215], v[36:39]
	v_mfma_f32_16x16x32_bf16 v[32:35], v[196:199], v[212:215], v[32:35]
	v_mfma_f32_16x16x32_bf16 v[20:23], v[188:191], v[220:223], v[20:23]
	v_mfma_f32_16x16x32_bf16 v[16:19], v[196:199], v[220:223], v[16:19]
	v_mfma_f32_16x16x32_bf16 v[4:7], v[188:191], v[228:231], v[4:7]
	v_mfma_f32_16x16x32_bf16 v[0:3], v[196:199], v[228:231], v[0:3]
	s_setprio 0
	s_barrier
	s_add_i32 s10, 0, 0x18000
	v_add_u32_e32 v144, s10, v171
	s_add_i32 s93, 0, 0x1c000
	ds_read_b128 v[132:135], v144
	ds_read_b128 v[158:161], v144 offset:1024
	ds_read_b128 v[162:165], v144 offset:2048
	ds_read_b128 v[166:169], v144 offset:3072
	v_add_u32_e32 v144, s93, v171
	ds_read_b128 v[184:187], v144
	ds_read_b128 v[188:191], v144 offset:1024
	ds_read_b128 v[192:195], v144 offset:2048
	ds_read_b128 v[196:199], v144 offset:3072
	s_add_u32 s62, s64, 0x40000
	s_addc_u32 s63, s65, 0
	s_mov_b32 m0, s67
	ds_read_b128 v[200:203], v181 offset:32768
	ds_read_b128 v[204:207], v181 offset:33792
	ds_read_b128 v[208:211], v181 offset:34816
	ds_read_b128 v[212:215], v181 offset:35840
	ds_read_b128 v[216:219], v181 offset:36864
	ds_read_b128 v[220:223], v181 offset:37888
	ds_read_b128 v[224:227], v181 offset:38912
	ds_read_b128 v[228:231], v181 offset:39936
	global_load_lds_dwordx4 v136, s[62:63]
	s_mov_b32 m0, s68
	s_nop 0
	global_load_lds_dwordx4 v140, s[62:63]
	s_waitcnt vmcnt(8)
	s_waitcnt lgkmcnt(0)
	s_barrier
	s_setprio 1
	s_waitcnt lgkmcnt(0)
	v_mfma_f32_16x16x32_bf16 v[124:127], v[132:135], v[200:203], v[124:127]
	v_mfma_f32_16x16x32_bf16 v[120:123], v[162:165], v[200:203], v[120:123]
	v_mfma_f32_16x16x32_bf16 v[108:111], v[132:135], v[208:211], v[108:111]
	v_mfma_f32_16x16x32_bf16 v[104:107], v[162:165], v[208:211], v[104:107]
	v_mfma_f32_16x16x32_bf16 v[92:95], v[132:135], v[216:219], v[92:95]
	v_mfma_f32_16x16x32_bf16 v[88:91], v[162:165], v[216:219], v[88:91]
	v_mfma_f32_16x16x32_bf16 v[76:79], v[132:135], v[224:227], v[76:79]
	v_mfma_f32_16x16x32_bf16 v[72:75], v[162:165], v[224:227], v[72:75]
	v_mfma_f32_16x16x32_bf16 v[124:127], v[158:161], v[204:207], v[124:127]
	v_mfma_f32_16x16x32_bf16 v[120:123], v[166:169], v[204:207], v[120:123]
	v_mfma_f32_16x16x32_bf16 v[108:111], v[158:161], v[212:215], v[108:111]
	v_mfma_f32_16x16x32_bf16 v[104:107], v[166:169], v[212:215], v[104:107]
	v_mfma_f32_16x16x32_bf16 v[92:95], v[158:161], v[220:223], v[92:95]
	v_mfma_f32_16x16x32_bf16 v[88:91], v[166:169], v[220:223], v[88:91]
	v_mfma_f32_16x16x32_bf16 v[76:79], v[158:161], v[228:231], v[76:79]
	v_mfma_f32_16x16x32_bf16 v[72:75], v[166:169], v[228:231], v[72:75]
	s_setprio 0
	s_setprio 1
	v_mfma_f32_16x16x32_bf16 v[116:119], v[184:187], v[200:203], v[116:119]
	v_mfma_f32_16x16x32_bf16 v[112:115], v[192:195], v[200:203], v[112:115]
	v_mfma_f32_16x16x32_bf16 v[100:103], v[184:187], v[208:211], v[100:103]
	v_mfma_f32_16x16x32_bf16 v[96:99], v[192:195], v[208:211], v[96:99]
	v_mfma_f32_16x16x32_bf16 v[84:87], v[184:187], v[216:219], v[84:87]
	v_mfma_f32_16x16x32_bf16 v[80:83], v[192:195], v[216:219], v[80:83]
	v_mfma_f32_16x16x32_bf16 v[68:71], v[184:187], v[224:227], v[68:71]
	v_mfma_f32_16x16x32_bf16 v[64:67], v[192:195], v[224:227], v[64:67]
	v_mfma_f32_16x16x32_bf16 v[116:119], v[188:191], v[204:207], v[116:119]
	v_mfma_f32_16x16x32_bf16 v[112:115], v[196:199], v[204:207], v[112:115]
	v_mfma_f32_16x16x32_bf16 v[100:103], v[188:191], v[212:215], v[100:103]
	v_mfma_f32_16x16x32_bf16 v[96:99], v[196:199], v[212:215], v[96:99]
	v_mfma_f32_16x16x32_bf16 v[84:87], v[188:191], v[220:223], v[84:87]
	v_mfma_f32_16x16x32_bf16 v[80:83], v[196:199], v[220:223], v[80:83]
	v_mfma_f32_16x16x32_bf16 v[68:71], v[188:191], v[228:231], v[68:71]
	v_mfma_f32_16x16x32_bf16 v[64:67], v[196:199], v[228:231], v[64:67]
	s_setprio 0
	s_barrier
	s_add_i32 s10, s10, s66
	s_mov_b32 m0, s10
	ds_read_b128 v[200:203], v181 offset:49152
	ds_read_b128 v[204:207], v181 offset:50176
	ds_read_b128 v[208:211], v181 offset:51200
	ds_read_b128 v[212:215], v181 offset:52224
	ds_read_b128 v[216:219], v181 offset:53248
	ds_read_b128 v[220:223], v181 offset:54272
	ds_read_b128 v[224:227], v181 offset:55296
	ds_read_b128 v[228:231], v181 offset:56320
	global_load_lds_dwordx4 v138, s[60:61]
	s_add_i32 m0, s10, 0x2000
	s_nop 0
	global_load_lds_dwordx4 v142, s[60:61]
	s_add_u32 s60, s60, 0x40000
	s_addc_u32 s61, s61, 0
	s_add_i32 s10, s93, s66
	s_mov_b32 m0, s10
	s_nop 0
	global_load_lds_dwordx4 v138, s[60:61]
	s_add_i32 m0, s10, 0x2000
	s_nop 0
	global_load_lds_dwordx4 v142, s[60:61]
	s_mov_b32 m0, s73
	s_nop 0
	global_load_lds_dwordx4 v136, s[58:59]
	v_lshl_add_u64 v[232:233], s[58:59], 0, v[140:141]
	s_mov_b32 m0, s78
	s_nop 0
	global_load_lds_dwordx4 v[232:233], off
	s_waitcnt vmcnt(8)
	s_waitcnt lgkmcnt(0)
	s_barrier
	s_setprio 1
	s_waitcnt lgkmcnt(0)
	v_mfma_f32_16x16x32_bf16 v[60:63], v[132:135], v[200:203], v[60:63]
	v_mfma_f32_16x16x32_bf16 v[56:59], v[162:165], v[200:203], v[56:59]
	v_mfma_f32_16x16x32_bf16 v[44:47], v[132:135], v[208:211], v[44:47]
	v_mfma_f32_16x16x32_bf16 v[40:43], v[162:165], v[208:211], v[40:43]
	v_mfma_f32_16x16x32_bf16 v[28:31], v[132:135], v[216:219], v[28:31]
	v_mfma_f32_16x16x32_bf16 v[24:27], v[162:165], v[216:219], v[24:27]
	v_mfma_f32_16x16x32_bf16 v[12:15], v[132:135], v[224:227], v[12:15]
	v_mfma_f32_16x16x32_bf16 v[8:11], v[162:165], v[224:227], v[8:11]
	v_mfma_f32_16x16x32_bf16 v[60:63], v[158:161], v[204:207], v[60:63]
	v_mfma_f32_16x16x32_bf16 v[56:59], v[166:169], v[204:207], v[56:59]
	v_mfma_f32_16x16x32_bf16 v[44:47], v[158:161], v[212:215], v[44:47]
	v_mfma_f32_16x16x32_bf16 v[40:43], v[166:169], v[212:215], v[40:43]
	v_mfma_f32_16x16x32_bf16 v[28:31], v[158:161], v[220:223], v[28:31]
	v_mfma_f32_16x16x32_bf16 v[24:27], v[166:169], v[220:223], v[24:27]
	v_mfma_f32_16x16x32_bf16 v[12:15], v[158:161], v[228:231], v[12:15]
	v_mfma_f32_16x16x32_bf16 v[8:11], v[166:169], v[228:231], v[8:11]
	s_setprio 0
	s_setprio 1
	v_mfma_f32_16x16x32_bf16 v[52:55], v[184:187], v[200:203], v[52:55]
	v_mfma_f32_16x16x32_bf16 v[48:51], v[192:195], v[200:203], v[48:51]
	v_mfma_f32_16x16x32_bf16 v[36:39], v[184:187], v[208:211], v[36:39]
	v_mfma_f32_16x16x32_bf16 v[32:35], v[192:195], v[208:211], v[32:35]
	v_mfma_f32_16x16x32_bf16 v[20:23], v[184:187], v[216:219], v[20:23]
	v_mfma_f32_16x16x32_bf16 v[16:19], v[192:195], v[216:219], v[16:19]
	v_mfma_f32_16x16x32_bf16 v[4:7], v[184:187], v[224:227], v[4:7]
	v_mfma_f32_16x16x32_bf16 v[0:3], v[192:195], v[224:227], v[0:3]
	v_mfma_f32_16x16x32_bf16 v[52:55], v[188:191], v[204:207], v[52:55]
	v_mfma_f32_16x16x32_bf16 v[48:51], v[196:199], v[204:207], v[48:51]
	v_mfma_f32_16x16x32_bf16 v[36:39], v[188:191], v[212:215], v[36:39]
	v_mfma_f32_16x16x32_bf16 v[32:35], v[196:199], v[212:215], v[32:35]
	v_mfma_f32_16x16x32_bf16 v[20:23], v[188:191], v[220:223], v[20:23]
	v_mfma_f32_16x16x32_bf16 v[16:19], v[196:199], v[220:223], v[16:19]
	v_mfma_f32_16x16x32_bf16 v[4:7], v[188:191], v[228:231], v[4:7]
	v_mfma_f32_16x16x32_bf16 v[0:3], v[196:199], v[228:231], v[0:3]
	s_setprio 0
	s_barrier
	s_add_i32 s10, s92, 2
	s_add_u32 s56, s56, 0x100
	s_addc_u32 s57, s57, 0
	s_cmp_gt_u32 s92, 13
	s_mov_b32 s92, s10
	s_cbranch_scc1 .LBB0_169
	s_branch .LBB0_163

.LBB0_713:
	s_add_u32 s19, s63, s6
	s_addc_u32 s29, s64, s7
	s_add_u32 s31, s65, s8
	s_addc_u32 s79, s66, s9
	s_ashr_i32 s23, s22, 31
	s_lshl_b64 s[6:7], s[22:23], 19
	s_add_u32 s24, s34, s6
	s_addc_u32 s25, s35, s7
	s_and_b64 s[8:9], s[4:5], exec
	s_cselect_b32 s23, s25, s45
	s_cselect_b32 s80, s24, s44
	s_ashr_i32 s21, s20, 31
	s_lshl_b64 s[8:9], s[20:21], 19
	s_add_u32 s26, s42, s8
	s_addc_u32 s27, s43, s9
	s_and_b64 s[36:37], s[4:5], exec
	s_cselect_b32 s21, s27, s39
	s_cselect_b32 s81, s26, s38
	s_add_u32 s36, s80, 0x80
	s_addc_u32 s37, s23, 0
	s_add_u32 s46, s81, 0x80
	s_addc_u32 s47, s21, 0
	v_lshl_add_u64 v[128:129], s[44:45], 0, v[156:157]
	v_lshl_add_u64 v[130:131], s[44:45], 0, v[158:159]
	s_mov_b32 s82, 0
	s_mov_b64 s[48:49], 0
	s_cmpk_eq_i32 s48, 0x700
	s_cselect_b64 s[54:55], -1, 0
	s_add_u32 s56, s44, s48
	s_addc_u32 s57, s45, s49
	s_add_u32 s84, s38, s48
	s_addc_u32 s83, s39, s49
	s_add_u32 s50, s56, 0x180
	s_addc_u32 s51, s57, 0
	s_add_u32 s52, s84, 0x180
	s_addc_u32 s53, s83, 0
	s_cmpk_eq_i32 s48, 0x700
	s_cselect_b32 s50, s36, s50
	s_cselect_b32 s51, s37, s51
	s_cselect_b32 s52, s46, s52
	s_cselect_b32 s53, s47, s53
	v_add_u32_e32 v164, s72, v171
	v_add_u32_e32 v168, s73, v171
	ds_read_b128 v[132:135], v164
	ds_read_b128 v[136:139], v164 offset:1024
	ds_read_b128 v[140:143], v164 offset:2048
	ds_read_b128 v[164:167], v164 offset:3072
	ds_read_b128 v[174:177], v168
	ds_read_b128 v[178:181], v168 offset:1024
	ds_read_b128 v[182:185], v168 offset:2048
	ds_read_b128 v[186:189], v168 offset:3072
	s_add_u32 s10, s56, 0x100
	s_addc_u32 s85, s57, 0
	s_and_b64 s[56:57], exec, s[54:55]
	s_cselect_b32 s57, s23, s85
	s_cselect_b32 s56, s80, s10
	s_add_u32 s10, s84, 0x100
	s_addc_u32 s83, s83, 0
	s_and_b64 s[54:55], exec, s[54:55]
	s_cselect_b32 s55, s21, s83
	s_cselect_b32 s54, s81, s10
	v_lshl_add_u64 v[168:169], v[128:129], 0, s[48:49]
	s_add_i32 m0, s59, 0xc000
	ds_read_b128 v[190:193], v172
	ds_read_b128 v[194:197], v172 offset:1024
	ds_read_b128 v[198:201], v172 offset:2048
	ds_read_b128 v[202:205], v172 offset:3072
	ds_read_b128 v[206:209], v172 offset:4096
	ds_read_b128 v[210:213], v172 offset:5120
	ds_read_b128 v[214:217], v172 offset:6144
	ds_read_b128 v[218:221], v172 offset:7168
	global_load_lds_dwordx4 v[168:169], off
	v_lshl_add_u64 v[168:169], v[130:131], 0, s[48:49]
	s_add_i32 m0, s59, 0xe000
	s_nop 0
	global_load_lds_dwordx4 v[168:169], off
	s_waitcnt vmcnt(8)
	s_waitcnt lgkmcnt(0)
	s_barrier
	s_setprio 1
	s_waitcnt lgkmcnt(0)
	v_mfma_f32_16x16x32_bf16 v[124:127], v[132:135], v[190:193], 0
	v_mfma_f32_16x16x32_bf16 v[120:123], v[140:143], v[190:193], 0
	v_mfma_f32_16x16x32_bf16 v[108:111], v[132:135], v[198:201], 0
	v_mfma_f32_16x16x32_bf16 v[104:107], v[140:143], v[198:201], 0
	v_mfma_f32_16x16x32_bf16 v[92:95], v[132:135], v[206:209], 0
	v_mfma_f32_16x16x32_bf16 v[88:91], v[140:143], v[206:209], 0
	v_mfma_f32_16x16x32_bf16 v[76:79], v[132:135], v[214:217], 0
	v_mfma_f32_16x16x32_bf16 v[72:75], v[140:143], v[214:217], 0
	v_mfma_f32_16x16x32_bf16 v[124:127], v[136:139], v[194:197], v[124:127]
	v_mfma_f32_16x16x32_bf16 v[120:123], v[164:167], v[194:197], v[120:123]
	v_mfma_f32_16x16x32_bf16 v[108:111], v[136:139], v[202:205], v[108:111]
	v_mfma_f32_16x16x32_bf16 v[104:107], v[164:167], v[202:205], v[104:107]
	v_mfma_f32_16x16x32_bf16 v[92:95], v[136:139], v[210:213], v[92:95]
	v_mfma_f32_16x16x32_bf16 v[88:91], v[164:167], v[210:213], v[88:91]
	v_mfma_f32_16x16x32_bf16 v[76:79], v[136:139], v[218:221], v[76:79]
	v_mfma_f32_16x16x32_bf16 v[72:75], v[164:167], v[218:221], v[72:75]
	s_setprio 0
	s_setprio 1
	v_mfma_f32_16x16x32_bf16 v[116:119], v[174:177], v[190:193], 0
	v_mfma_f32_16x16x32_bf16 v[112:115], v[182:185], v[190:193], 0
	v_mfma_f32_16x16x32_bf16 v[100:103], v[174:177], v[198:201], 0
	v_mfma_f32_16x16x32_bf16 v[96:99], v[182:185], v[198:201], 0
	v_mfma_f32_16x16x32_bf16 v[84:87], v[174:177], v[206:209], 0
	v_mfma_f32_16x16x32_bf16 v[80:83], v[182:185], v[206:209], 0
	v_mfma_f32_16x16x32_bf16 v[68:71], v[174:177], v[214:217], 0
	v_mfma_f32_16x16x32_bf16 v[64:67], v[182:185], v[214:217], 0
	v_mfma_f32_16x16x32_bf16 v[116:119], v[178:181], v[194:197], v[116:119]
	v_mfma_f32_16x16x32_bf16 v[112:115], v[186:189], v[194:197], v[112:115]
	v_mfma_f32_16x16x32_bf16 v[100:103], v[178:181], v[202:205], v[100:103]
	v_mfma_f32_16x16x32_bf16 v[96:99], v[186:189], v[202:205], v[96:99]
	v_mfma_f32_16x16x32_bf16 v[84:87], v[178:181], v[210:213], v[84:87]
	v_mfma_f32_16x16x32_bf16 v[80:83], v[186:189], v[210:213], v[80:83]
	v_mfma_f32_16x16x32_bf16 v[68:71], v[178:181], v[218:221], v[68:71]
	v_mfma_f32_16x16x32_bf16 v[64:67], v[186:189], v[218:221], v[64:67]
	s_setprio 0
	s_barrier
	s_add_i32 s10, s72, s58
	s_mov_b32 m0, s10
	ds_read_b128 v[190:193], v172 offset:16384
	ds_read_b128 v[194:197], v172 offset:17408
	ds_read_b128 v[198:201], v172 offset:18432
	ds_read_b128 v[202:205], v172 offset:19456
	ds_read_b128 v[206:209], v172 offset:20480
	ds_read_b128 v[210:213], v172 offset:21504
	ds_read_b128 v[214:217], v172 offset:22528
	ds_read_b128 v[218:221], v172 offset:23552
	global_load_lds_dwordx4 v146, s[54:55]
	s_add_i32 m0, s10, 0x2000
	s_nop 0
	global_load_lds_dwordx4 v150, s[54:55]
	s_add_u32 s54, s54, 0x40000
	s_addc_u32 s55, s55, 0
	s_add_i32 s10, s73, s58
	s_mov_b32 m0, s10
	s_nop 0
	global_load_lds_dwordx4 v146, s[54:55]
	s_add_i32 m0, s10, 0x2000
	s_nop 0
	global_load_lds_dwordx4 v150, s[54:55]
	s_mov_b32 m0, s59
	s_nop 0
	global_load_lds_dwordx4 v144, s[56:57]
	s_mov_b32 m0, s60
	s_nop 0
	global_load_lds_dwordx4 v148, s[56:57]
	s_waitcnt vmcnt(8)
	s_waitcnt lgkmcnt(0)
	s_barrier
	s_setprio 1
	s_waitcnt lgkmcnt(0)
	v_mfma_f32_16x16x32_bf16 v[60:63], v[132:135], v[190:193], 0
	v_mfma_f32_16x16x32_bf16 v[56:59], v[140:143], v[190:193], 0
	v_mfma_f32_16x16x32_bf16 v[44:47], v[132:135], v[198:201], 0
	v_mfma_f32_16x16x32_bf16 v[40:43], v[140:143], v[198:201], 0
	v_mfma_f32_16x16x32_bf16 v[28:31], v[132:135], v[206:209], 0
	v_mfma_f32_16x16x32_bf16 v[24:27], v[140:143], v[206:209], 0
	v_mfma_f32_16x16x32_bf16 v[12:15], v[132:135], v[214:217], 0
	v_mfma_f32_16x16x32_bf16 v[8:11], v[140:143], v[214:217], 0
	v_mfma_f32_16x16x32_bf16 v[60:63], v[136:139], v[194:197], v[60:63]
	v_mfma_f32_16x16x32_bf16 v[56:59], v[164:167], v[194:197], v[56:59]
	v_mfma_f32_16x16x32_bf16 v[44:47], v[136:139], v[202:205], v[44:47]
	v_mfma_f32_16x16x32_bf16 v[40:43], v[164:167], v[202:205], v[40:43]
	v_mfma_f32_16x16x32_bf16 v[28:31], v[136:139], v[210:213], v[28:31]
	v_mfma_f32_16x16x32_bf16 v[24:27], v[164:167], v[210:213], v[24:27]
	v_mfma_f32_16x16x32_bf16 v[12:15], v[136:139], v[218:221], v[12:15]
	v_mfma_f32_16x16x32_bf16 v[8:11], v[164:167], v[218:221], v[8:11]
	s_setprio 0
	s_setprio 1
	v_mfma_f32_16x16x32_bf16 v[52:55], v[174:177], v[190:193], 0
	v_mfma_f32_16x16x32_bf16 v[48:51], v[182:185], v[190:193], 0
	v_mfma_f32_16x16x32_bf16 v[36:39], v[174:177], v[198:201], 0
	v_mfma_f32_16x16x32_bf16 v[32:35], v[182:185], v[198:201], 0
	v_mfma_f32_16x16x32_bf16 v[20:23], v[174:177], v[206:209], 0
	v_mfma_f32_16x16x32_bf16 v[16:19], v[182:185], v[206:209], 0
	v_mfma_f32_16x16x32_bf16 v[4:7], v[174:177], v[214:217], 0
	v_mfma_f32_16x16x32_bf16 v[0:3], v[182:185], v[214:217], 0
	v_mfma_f32_16x16x32_bf16 v[52:55], v[178:181], v[194:197], v[52:55]
	v_mfma_f32_16x16x32_bf16 v[48:51], v[186:189], v[194:197], v[48:51]
	v_mfma_f32_16x16x32_bf16 v[36:39], v[178:181], v[202:205], v[36:39]
	v_mfma_f32_16x16x32_bf16 v[32:35], v[186:189], v[202:205], v[32:35]
	v_mfma_f32_16x16x32_bf16 v[20:23], v[178:181], v[210:213], v[20:23]
	v_mfma_f32_16x16x32_bf16 v[16:19], v[186:189], v[210:213], v[16:19]
	v_mfma_f32_16x16x32_bf16 v[4:7], v[178:181], v[218:221], v[4:7]
	v_mfma_f32_16x16x32_bf16 v[0:3], v[186:189], v[218:221], v[0:3]
	s_setprio 0
	s_barrier
	s_add_i32 s10, 0, 0x18000
	s_add_i32 s83, 0, 0x1c000
	v_add_u32_e32 v164, s10, v171
	v_add_u32_e32 v168, s83, v171
	ds_read_b128 v[132:135], v164
	ds_read_b128 v[136:139], v164 offset:1024
	ds_read_b128 v[140:143], v164 offset:2048
	ds_read_b128 v[164:167], v164 offset:3072
	ds_read_b128 v[174:177], v168
	ds_read_b128 v[178:181], v168 offset:1024
	ds_read_b128 v[182:185], v168 offset:2048
	ds_read_b128 v[186:189], v168 offset:3072
	s_add_u32 s54, s56, 0x40000
	s_addc_u32 s55, s57, 0
	s_mov_b32 m0, s61
	ds_read_b128 v[190:193], v172 offset:32768
	ds_read_b128 v[194:197], v172 offset:33792
	ds_read_b128 v[198:201], v172 offset:34816
	ds_read_b128 v[202:205], v172 offset:35840
	ds_read_b128 v[206:209], v172 offset:36864
	ds_read_b128 v[210:213], v172 offset:37888
	ds_read_b128 v[214:217], v172 offset:38912
	ds_read_b128 v[218:221], v172 offset:39936
	global_load_lds_dwordx4 v144, s[54:55]
	s_mov_b32 m0, s62
	s_nop 0
	global_load_lds_dwordx4 v148, s[54:55]
	s_waitcnt vmcnt(8)
	s_waitcnt lgkmcnt(0)
	s_barrier
	s_setprio 1
	s_waitcnt lgkmcnt(0)
	v_mfma_f32_16x16x32_bf16 v[124:127], v[132:135], v[190:193], v[124:127]
	v_mfma_f32_16x16x32_bf16 v[120:123], v[140:143], v[190:193], v[120:123]
	v_mfma_f32_16x16x32_bf16 v[108:111], v[132:135], v[198:201], v[108:111]
	v_mfma_f32_16x16x32_bf16 v[104:107], v[140:143], v[198:201], v[104:107]
	v_mfma_f32_16x16x32_bf16 v[92:95], v[132:135], v[206:209], v[92:95]
	v_mfma_f32_16x16x32_bf16 v[88:91], v[140:143], v[206:209], v[88:91]
	v_mfma_f32_16x16x32_bf16 v[76:79], v[132:135], v[214:217], v[76:79]
	v_mfma_f32_16x16x32_bf16 v[72:75], v[140:143], v[214:217], v[72:75]
	v_mfma_f32_16x16x32_bf16 v[124:127], v[136:139], v[194:197], v[124:127]
	v_mfma_f32_16x16x32_bf16 v[120:123], v[164:167], v[194:197], v[120:123]
	v_mfma_f32_16x16x32_bf16 v[108:111], v[136:139], v[202:205], v[108:111]
	v_mfma_f32_16x16x32_bf16 v[104:107], v[164:167], v[202:205], v[104:107]
	v_mfma_f32_16x16x32_bf16 v[92:95], v[136:139], v[210:213], v[92:95]
	v_mfma_f32_16x16x32_bf16 v[88:91], v[164:167], v[210:213], v[88:91]
	v_mfma_f32_16x16x32_bf16 v[76:79], v[136:139], v[218:221], v[76:79]
	v_mfma_f32_16x16x32_bf16 v[72:75], v[164:167], v[218:221], v[72:75]
	s_setprio 0
	s_setprio 1
	v_mfma_f32_16x16x32_bf16 v[116:119], v[174:177], v[190:193], v[116:119]
	v_mfma_f32_16x16x32_bf16 v[112:115], v[182:185], v[190:193], v[112:115]
	v_mfma_f32_16x16x32_bf16 v[100:103], v[174:177], v[198:201], v[100:103]
	v_mfma_f32_16x16x32_bf16 v[96:99], v[182:185], v[198:201], v[96:99]
	v_mfma_f32_16x16x32_bf16 v[84:87], v[174:177], v[206:209], v[84:87]
	v_mfma_f32_16x16x32_bf16 v[80:83], v[182:185], v[206:209], v[80:83]
	v_mfma_f32_16x16x32_bf16 v[68:71], v[174:177], v[214:217], v[68:71]
	v_mfma_f32_16x16x32_bf16 v[64:67], v[182:185], v[214:217], v[64:67]
	v_mfma_f32_16x16x32_bf16 v[116:119], v[178:181], v[194:197], v[116:119]
	v_mfma_f32_16x16x32_bf16 v[112:115], v[186:189], v[194:197], v[112:115]
	v_mfma_f32_16x16x32_bf16 v[100:103], v[178:181], v[202:205], v[100:103]
	v_mfma_f32_16x16x32_bf16 v[96:99], v[186:189], v[202:205], v[96:99]
	v_mfma_f32_16x16x32_bf16 v[84:87], v[178:181], v[210:213], v[84:87]
	v_mfma_f32_16x16x32_bf16 v[80:83], v[186:189], v[210:213], v[80:83]
	v_mfma_f32_16x16x32_bf16 v[68:71], v[178:181], v[218:221], v[68:71]
	v_mfma_f32_16x16x32_bf16 v[64:67], v[186:189], v[218:221], v[64:67]
	s_setprio 0
	s_barrier
	s_add_i32 s10, s10, s58
	s_mov_b32 m0, s10
	ds_read_b128 v[190:193], v172 offset:49152
	ds_read_b128 v[194:197], v172 offset:50176
	ds_read_b128 v[198:201], v172 offset:51200
	ds_read_b128 v[202:205], v172 offset:52224
	ds_read_b128 v[206:209], v172 offset:53248
	ds_read_b128 v[210:213], v172 offset:54272
	ds_read_b128 v[214:217], v172 offset:55296
	ds_read_b128 v[218:221], v172 offset:56320
	global_load_lds_dwordx4 v146, s[52:53]
	s_add_i32 m0, s10, 0x2000
	s_nop 0
	global_load_lds_dwordx4 v150, s[52:53]
	s_add_u32 s52, s52, 0x40000
	s_addc_u32 s53, s53, 0
	s_add_i32 s10, s83, s58
	s_mov_b32 m0, s10
	s_nop 0
	global_load_lds_dwordx4 v146, s[52:53]
	s_add_i32 m0, s10, 0x2000
	s_nop 0
	global_load_lds_dwordx4 v150, s[52:53]
	s_mov_b32 m0, s68
	s_nop 0
	global_load_lds_dwordx4 v144, s[50:51]
	s_mov_b32 m0, s69
	s_nop 0
	global_load_lds_dwordx4 v148, s[50:51]
	s_waitcnt vmcnt(8)
	s_waitcnt lgkmcnt(0)
	s_barrier
	s_setprio 1
	s_waitcnt lgkmcnt(0)
	v_mfma_f32_16x16x32_bf16 v[60:63], v[132:135], v[190:193], v[60:63]
	v_mfma_f32_16x16x32_bf16 v[56:59], v[140:143], v[190:193], v[56:59]
	v_mfma_f32_16x16x32_bf16 v[44:47], v[132:135], v[198:201], v[44:47]
	v_mfma_f32_16x16x32_bf16 v[40:43], v[140:143], v[198:201], v[40:43]
	v_mfma_f32_16x16x32_bf16 v[28:31], v[132:135], v[206:209], v[28:31]
	v_mfma_f32_16x16x32_bf16 v[24:27], v[140:143], v[206:209], v[24:27]
	v_mfma_f32_16x16x32_bf16 v[12:15], v[132:135], v[214:217], v[12:15]
	v_mfma_f32_16x16x32_bf16 v[8:11], v[140:143], v[214:217], v[8:11]
	v_mfma_f32_16x16x32_bf16 v[60:63], v[136:139], v[194:197], v[60:63]
	v_mfma_f32_16x16x32_bf16 v[56:59], v[164:167], v[194:197], v[56:59]
	v_mfma_f32_16x16x32_bf16 v[44:47], v[136:139], v[202:205], v[44:47]
	v_mfma_f32_16x16x32_bf16 v[40:43], v[164:167], v[202:205], v[40:43]
	v_mfma_f32_16x16x32_bf16 v[28:31], v[136:139], v[210:213], v[28:31]
	v_mfma_f32_16x16x32_bf16 v[24:27], v[164:167], v[210:213], v[24:27]
	v_mfma_f32_16x16x32_bf16 v[12:15], v[136:139], v[218:221], v[12:15]
	v_mfma_f32_16x16x32_bf16 v[8:11], v[164:167], v[218:221], v[8:11]
	s_setprio 0
	s_setprio 1
	v_mfma_f32_16x16x32_bf16 v[52:55], v[174:177], v[190:193], v[52:55]
	v_mfma_f32_16x16x32_bf16 v[48:51], v[182:185], v[190:193], v[48:51]
	v_mfma_f32_16x16x32_bf16 v[36:39], v[174:177], v[198:201], v[36:39]
	v_mfma_f32_16x16x32_bf16 v[32:35], v[182:185], v[198:201], v[32:35]
	v_mfma_f32_16x16x32_bf16 v[20:23], v[174:177], v[206:209], v[20:23]
	v_mfma_f32_16x16x32_bf16 v[16:19], v[182:185], v[206:209], v[16:19]
	v_mfma_f32_16x16x32_bf16 v[4:7], v[174:177], v[214:217], v[4:7]
	v_mfma_f32_16x16x32_bf16 v[0:3], v[182:185], v[214:217], v[0:3]
	v_mfma_f32_16x16x32_bf16 v[52:55], v[178:181], v[194:197], v[52:55]
	v_mfma_f32_16x16x32_bf16 v[48:51], v[186:189], v[194:197], v[48:51]
	v_mfma_f32_16x16x32_bf16 v[36:39], v[178:181], v[202:205], v[36:39]
	v_mfma_f32_16x16x32_bf16 v[32:35], v[186:189], v[202:205], v[32:35]
	v_mfma_f32_16x16x32_bf16 v[20:23], v[178:181], v[210:213], v[20:23]
	v_mfma_f32_16x16x32_bf16 v[16:19], v[186:189], v[210:213], v[16:19]
	v_mfma_f32_16x16x32_bf16 v[4:7], v[178:181], v[218:221], v[4:7]
	v_mfma_f32_16x16x32_bf16 v[0:3], v[186:189], v[218:221], v[0:3]
	s_setprio 0
	s_barrier
	s_add_i32 s10, s82, 2
	s_add_u32 s48, s48, 0x100
	s_addc_u32 s49, s49, 0
	s_cmp_gt_u32 s82, 13
	s_mov_b32 s82, s10
	s_cbranch_scc1 .LBB0_721
	s_branch .LBB0_715

.LBB0_805:
	s_add_u32 s27, s61, s4
	s_addc_u32 s72, s62, s5
	s_add_u32 s73, s63, s6
	s_addc_u32 s78, s64, s7
	s_ashr_i32 s21, s20, 31
	s_lshl_b64 s[4:5], s[20:21], 19
	s_add_u32 s22, s40, s4
	s_addc_u32 s23, s41, s5
	s_and_b64 s[6:7], s[0:1], exec
	s_cselect_b32 s21, s23, s31
	s_cselect_b32 s79, s22, s30
	s_ashr_i32 s19, s18, 31
	s_lshl_b64 s[6:7], s[18:19], 19
	s_add_u32 s24, s42, s6
	s_addc_u32 s25, s43, s7
	s_and_b64 s[36:37], s[0:1], exec
	s_cselect_b32 s19, s25, s29
	s_cselect_b32 s80, s24, s28
	s_add_u32 s36, s79, 0x80
	s_addc_u32 s37, s21, 0
	s_add_u32 s38, s80, 0x80
	s_addc_u32 s39, s19, 0
	v_lshl_add_u64 v[148:149], s[30:31], 0, v[140:141]
	v_lshl_add_u64 v[150:151], s[30:31], 0, v[142:143]
	s_mov_b32 s81, 0
	s_mov_b64 s[44:45], 0
	s_cmpk_eq_i32 s44, 0x700
	s_cselect_b64 s[50:51], -1, 0
	s_add_u32 s52, s30, s44
	s_addc_u32 s53, s31, s45
	s_add_u32 s83, s28, s44
	s_addc_u32 s82, s29, s45
	s_add_u32 s46, s52, 0x180
	s_addc_u32 s47, s53, 0
	s_add_u32 s48, s83, 0x180
	s_addc_u32 s49, s82, 0
	s_cmpk_eq_i32 s44, 0x700
	s_cselect_b32 s46, s36, s46
	s_cselect_b32 s47, s37, s47
	s_cselect_b32 s48, s38, s48
	s_cselect_b32 s49, s39, s49
	v_add_u32_e32 v152, s68, v157
	ds_read_b128 v[166:169], v152
	ds_read_b128 v[170:173], v152 offset:1024
	ds_read_b128 v[174:177], v152 offset:2048
	ds_read_b128 v[178:181], v152 offset:3072
	v_add_u32_e32 v152, s69, v157
	ds_read_b128 v[182:185], v152
	ds_read_b128 v[186:189], v152 offset:1024
	ds_read_b128 v[190:193], v152 offset:2048
	ds_read_b128 v[194:197], v152 offset:3072
	s_add_u32 s8, s52, 0x100
	s_addc_u32 s84, s53, 0
	s_and_b64 s[52:53], exec, s[50:51]
	s_cselect_b32 s53, s21, s84
	s_cselect_b32 s52, s79, s8
	s_add_u32 s8, s83, 0x100
	s_addc_u32 s82, s82, 0
	s_and_b64 s[50:51], exec, s[50:51]
	s_cselect_b32 s51, s19, s82
	s_cselect_b32 s50, s80, s8
	v_lshl_add_u64 v[154:155], v[148:149], 0, s[44:45]
	s_add_i32 m0, s57, 0xc000
	ds_read_b128 v[198:201], v161
	ds_read_b128 v[202:205], v161 offset:1024
	ds_read_b128 v[206:209], v161 offset:2048
	ds_read_b128 v[210:213], v161 offset:3072
	ds_read_b128 v[214:217], v161 offset:4096
	ds_read_b128 v[218:221], v161 offset:5120
	ds_read_b128 v[222:225], v161 offset:6144
	ds_read_b128 v[226:229], v161 offset:7168
	global_load_lds_dwordx4 v[154:155], off
	v_lshl_add_u64 v[154:155], v[150:151], 0, s[44:45]
	s_add_i32 m0, s57, 0xe000
	s_nop 0
	global_load_lds_dwordx4 v[154:155], off
	s_waitcnt vmcnt(8)
	s_waitcnt lgkmcnt(0)
	s_barrier
	s_setprio 1
	s_waitcnt lgkmcnt(0)
	v_mfma_f32_16x16x32_bf16 v[124:127], v[166:169], v[198:201], 0
	v_mfma_f32_16x16x32_bf16 v[120:123], v[174:177], v[198:201], 0
	v_mfma_f32_16x16x32_bf16 v[108:111], v[166:169], v[206:209], 0
	v_mfma_f32_16x16x32_bf16 v[104:107], v[174:177], v[206:209], 0
	v_mfma_f32_16x16x32_bf16 v[92:95], v[166:169], v[214:217], 0
	v_mfma_f32_16x16x32_bf16 v[88:91], v[174:177], v[214:217], 0
	v_mfma_f32_16x16x32_bf16 v[76:79], v[166:169], v[222:225], 0
	v_mfma_f32_16x16x32_bf16 v[72:75], v[174:177], v[222:225], 0
	v_mfma_f32_16x16x32_bf16 v[124:127], v[170:173], v[202:205], v[124:127]
	v_mfma_f32_16x16x32_bf16 v[120:123], v[178:181], v[202:205], v[120:123]
	v_mfma_f32_16x16x32_bf16 v[108:111], v[170:173], v[210:213], v[108:111]
	v_mfma_f32_16x16x32_bf16 v[104:107], v[178:181], v[210:213], v[104:107]
	v_mfma_f32_16x16x32_bf16 v[92:95], v[170:173], v[218:221], v[92:95]
	v_mfma_f32_16x16x32_bf16 v[88:91], v[178:181], v[218:221], v[88:91]
	v_mfma_f32_16x16x32_bf16 v[76:79], v[170:173], v[226:229], v[76:79]
	v_mfma_f32_16x16x32_bf16 v[72:75], v[178:181], v[226:229], v[72:75]
	s_setprio 0
	s_setprio 1
	v_mfma_f32_16x16x32_bf16 v[116:119], v[182:185], v[198:201], 0
	v_mfma_f32_16x16x32_bf16 v[112:115], v[190:193], v[198:201], 0
	v_mfma_f32_16x16x32_bf16 v[100:103], v[182:185], v[206:209], 0
	v_mfma_f32_16x16x32_bf16 v[96:99], v[190:193], v[206:209], 0
	v_mfma_f32_16x16x32_bf16 v[84:87], v[182:185], v[214:217], 0
	v_mfma_f32_16x16x32_bf16 v[80:83], v[190:193], v[214:217], 0
	v_mfma_f32_16x16x32_bf16 v[68:71], v[182:185], v[222:225], 0
	v_mfma_f32_16x16x32_bf16 v[64:67], v[190:193], v[222:225], 0
	v_mfma_f32_16x16x32_bf16 v[116:119], v[186:189], v[202:205], v[116:119]
	v_mfma_f32_16x16x32_bf16 v[112:115], v[194:197], v[202:205], v[112:115]
	v_mfma_f32_16x16x32_bf16 v[100:103], v[186:189], v[210:213], v[100:103]
	v_mfma_f32_16x16x32_bf16 v[96:99], v[194:197], v[210:213], v[96:99]
	v_mfma_f32_16x16x32_bf16 v[84:87], v[186:189], v[218:221], v[84:87]
	v_mfma_f32_16x16x32_bf16 v[80:83], v[194:197], v[218:221], v[80:83]
	v_mfma_f32_16x16x32_bf16 v[68:71], v[186:189], v[226:229], v[68:71]
	v_mfma_f32_16x16x32_bf16 v[64:67], v[194:197], v[226:229], v[64:67]
	s_setprio 0
	s_barrier
	s_add_i32 s8, s68, s54
	s_mov_b32 m0, s8
	ds_read_b128 v[198:201], v161 offset:16384
	ds_read_b128 v[202:205], v161 offset:17408
	ds_read_b128 v[206:209], v161 offset:18432
	ds_read_b128 v[210:213], v161 offset:19456
	ds_read_b128 v[214:217], v161 offset:20480
	ds_read_b128 v[218:221], v161 offset:21504
	ds_read_b128 v[222:225], v161 offset:22528
	ds_read_b128 v[226:229], v161 offset:23552
	global_load_lds_dwordx4 v128, s[50:51]
	s_add_i32 m0, s8, 0x2000
	s_nop 0
	global_load_lds_dwordx4 v130, s[50:51]
	s_add_u32 s50, s50, 0x40000
	s_addc_u32 s51, s51, 0
	s_add_i32 s8, s69, s54
	s_mov_b32 m0, s8
	s_nop 0
	global_load_lds_dwordx4 v128, s[50:51]
	s_add_i32 m0, s8, 0x2000
	s_nop 0
	global_load_lds_dwordx4 v130, s[50:51]
	s_mov_b32 m0, s57
	s_nop 0
	global_load_lds_dwordx4 v134, s[52:53]
	s_mov_b32 m0, s58
	s_nop 0
	global_load_lds_dwordx4 v132, s[52:53]
	s_waitcnt vmcnt(8)
	s_waitcnt lgkmcnt(0)
	s_barrier
	s_setprio 1
	s_waitcnt lgkmcnt(0)
	v_mfma_f32_16x16x32_bf16 v[60:63], v[166:169], v[198:201], 0
	v_mfma_f32_16x16x32_bf16 v[56:59], v[174:177], v[198:201], 0
	v_mfma_f32_16x16x32_bf16 v[44:47], v[166:169], v[206:209], 0
	v_mfma_f32_16x16x32_bf16 v[40:43], v[174:177], v[206:209], 0
	v_mfma_f32_16x16x32_bf16 v[28:31], v[166:169], v[214:217], 0
	v_mfma_f32_16x16x32_bf16 v[24:27], v[174:177], v[214:217], 0
	v_mfma_f32_16x16x32_bf16 v[12:15], v[166:169], v[222:225], 0
	v_mfma_f32_16x16x32_bf16 v[8:11], v[174:177], v[222:225], 0
	v_mfma_f32_16x16x32_bf16 v[60:63], v[170:173], v[202:205], v[60:63]
	v_mfma_f32_16x16x32_bf16 v[56:59], v[178:181], v[202:205], v[56:59]
	v_mfma_f32_16x16x32_bf16 v[44:47], v[170:173], v[210:213], v[44:47]
	v_mfma_f32_16x16x32_bf16 v[40:43], v[178:181], v[210:213], v[40:43]
	v_mfma_f32_16x16x32_bf16 v[28:31], v[170:173], v[218:221], v[28:31]
	v_mfma_f32_16x16x32_bf16 v[24:27], v[178:181], v[218:221], v[24:27]
	v_mfma_f32_16x16x32_bf16 v[12:15], v[170:173], v[226:229], v[12:15]
	v_mfma_f32_16x16x32_bf16 v[8:11], v[178:181], v[226:229], v[8:11]
	s_setprio 0
	s_setprio 1
	v_mfma_f32_16x16x32_bf16 v[52:55], v[182:185], v[198:201], 0
	v_mfma_f32_16x16x32_bf16 v[48:51], v[190:193], v[198:201], 0
	v_mfma_f32_16x16x32_bf16 v[36:39], v[182:185], v[206:209], 0
	v_mfma_f32_16x16x32_bf16 v[32:35], v[190:193], v[206:209], 0
	v_mfma_f32_16x16x32_bf16 v[20:23], v[182:185], v[214:217], 0
	v_mfma_f32_16x16x32_bf16 v[16:19], v[190:193], v[214:217], 0
	v_mfma_f32_16x16x32_bf16 v[4:7], v[182:185], v[222:225], 0
	v_mfma_f32_16x16x32_bf16 v[0:3], v[190:193], v[222:225], 0
	v_mfma_f32_16x16x32_bf16 v[52:55], v[186:189], v[202:205], v[52:55]
	v_mfma_f32_16x16x32_bf16 v[48:51], v[194:197], v[202:205], v[48:51]
	v_mfma_f32_16x16x32_bf16 v[36:39], v[186:189], v[210:213], v[36:39]
	v_mfma_f32_16x16x32_bf16 v[32:35], v[194:197], v[210:213], v[32:35]
	v_mfma_f32_16x16x32_bf16 v[20:23], v[186:189], v[218:221], v[20:23]
	v_mfma_f32_16x16x32_bf16 v[16:19], v[194:197], v[218:221], v[16:19]
	v_mfma_f32_16x16x32_bf16 v[4:7], v[186:189], v[226:229], v[4:7]
	v_mfma_f32_16x16x32_bf16 v[0:3], v[194:197], v[226:229], v[0:3]
	s_setprio 0
	s_barrier
	s_add_i32 s8, 0, 0x18000
	v_add_u32_e32 v152, s8, v157
	s_add_i32 s82, 0, 0x1c000
	ds_read_b128 v[166:169], v152
	ds_read_b128 v[170:173], v152 offset:1024
	ds_read_b128 v[174:177], v152 offset:2048
	ds_read_b128 v[178:181], v152 offset:3072
	v_add_u32_e32 v152, s82, v157
	ds_read_b128 v[182:185], v152
	ds_read_b128 v[186:189], v152 offset:1024
	ds_read_b128 v[190:193], v152 offset:2048
	ds_read_b128 v[194:197], v152 offset:3072
	s_add_u32 s50, s52, 0x40000
	s_addc_u32 s51, s53, 0
	s_mov_b32 m0, s59
	ds_read_b128 v[198:201], v161 offset:32768
	ds_read_b128 v[202:205], v161 offset:33792
	ds_read_b128 v[206:209], v161 offset:34816
	ds_read_b128 v[210:213], v161 offset:35840
	ds_read_b128 v[214:217], v161 offset:36864
	ds_read_b128 v[218:221], v161 offset:37888
	ds_read_b128 v[222:225], v161 offset:38912
	ds_read_b128 v[226:229], v161 offset:39936
	global_load_lds_dwordx4 v134, s[50:51]
	s_mov_b32 m0, s60
	s_nop 0
	global_load_lds_dwordx4 v132, s[50:51]
	s_waitcnt vmcnt(8)
	s_waitcnt lgkmcnt(0)
	s_barrier
	s_setprio 1
	s_waitcnt lgkmcnt(0)
	v_mfma_f32_16x16x32_bf16 v[124:127], v[166:169], v[198:201], v[124:127]
	v_mfma_f32_16x16x32_bf16 v[120:123], v[174:177], v[198:201], v[120:123]
	v_mfma_f32_16x16x32_bf16 v[108:111], v[166:169], v[206:209], v[108:111]
	v_mfma_f32_16x16x32_bf16 v[104:107], v[174:177], v[206:209], v[104:107]
	v_mfma_f32_16x16x32_bf16 v[92:95], v[166:169], v[214:217], v[92:95]
	v_mfma_f32_16x16x32_bf16 v[88:91], v[174:177], v[214:217], v[88:91]
	v_mfma_f32_16x16x32_bf16 v[76:79], v[166:169], v[222:225], v[76:79]
	v_mfma_f32_16x16x32_bf16 v[72:75], v[174:177], v[222:225], v[72:75]
	v_mfma_f32_16x16x32_bf16 v[124:127], v[170:173], v[202:205], v[124:127]
	v_mfma_f32_16x16x32_bf16 v[120:123], v[178:181], v[202:205], v[120:123]
	v_mfma_f32_16x16x32_bf16 v[108:111], v[170:173], v[210:213], v[108:111]
	v_mfma_f32_16x16x32_bf16 v[104:107], v[178:181], v[210:213], v[104:107]
	v_mfma_f32_16x16x32_bf16 v[92:95], v[170:173], v[218:221], v[92:95]
	v_mfma_f32_16x16x32_bf16 v[88:91], v[178:181], v[218:221], v[88:91]
	v_mfma_f32_16x16x32_bf16 v[76:79], v[170:173], v[226:229], v[76:79]
	v_mfma_f32_16x16x32_bf16 v[72:75], v[178:181], v[226:229], v[72:75]
	s_setprio 0
	s_setprio 1
	v_mfma_f32_16x16x32_bf16 v[116:119], v[182:185], v[198:201], v[116:119]
	v_mfma_f32_16x16x32_bf16 v[112:115], v[190:193], v[198:201], v[112:115]
	v_mfma_f32_16x16x32_bf16 v[100:103], v[182:185], v[206:209], v[100:103]
	v_mfma_f32_16x16x32_bf16 v[96:99], v[190:193], v[206:209], v[96:99]
	v_mfma_f32_16x16x32_bf16 v[84:87], v[182:185], v[214:217], v[84:87]
	v_mfma_f32_16x16x32_bf16 v[80:83], v[190:193], v[214:217], v[80:83]
	v_mfma_f32_16x16x32_bf16 v[68:71], v[182:185], v[222:225], v[68:71]
	v_mfma_f32_16x16x32_bf16 v[64:67], v[190:193], v[222:225], v[64:67]
	v_mfma_f32_16x16x32_bf16 v[116:119], v[186:189], v[202:205], v[116:119]
	v_mfma_f32_16x16x32_bf16 v[112:115], v[194:197], v[202:205], v[112:115]
	v_mfma_f32_16x16x32_bf16 v[100:103], v[186:189], v[210:213], v[100:103]
	v_mfma_f32_16x16x32_bf16 v[96:99], v[194:197], v[210:213], v[96:99]
	v_mfma_f32_16x16x32_bf16 v[84:87], v[186:189], v[218:221], v[84:87]
	v_mfma_f32_16x16x32_bf16 v[80:83], v[194:197], v[218:221], v[80:83]
	v_mfma_f32_16x16x32_bf16 v[68:71], v[186:189], v[226:229], v[68:71]
	v_mfma_f32_16x16x32_bf16 v[64:67], v[194:197], v[226:229], v[64:67]
	s_setprio 0
	s_barrier
	s_add_i32 s8, s8, s54
	s_mov_b32 m0, s8
	ds_read_b128 v[198:201], v161 offset:49152
	ds_read_b128 v[202:205], v161 offset:50176
	ds_read_b128 v[206:209], v161 offset:51200
	ds_read_b128 v[210:213], v161 offset:52224
	ds_read_b128 v[214:217], v161 offset:53248
	ds_read_b128 v[218:221], v161 offset:54272
	ds_read_b128 v[222:225], v161 offset:55296
	ds_read_b128 v[226:229], v161 offset:56320
	global_load_lds_dwordx4 v128, s[48:49]
	s_add_i32 m0, s8, 0x2000
	s_nop 0
	global_load_lds_dwordx4 v130, s[48:49]
	s_add_u32 s48, s48, 0x40000
	s_addc_u32 s49, s49, 0
	s_add_i32 s8, s82, s54
	s_mov_b32 m0, s8
	s_nop 0
	global_load_lds_dwordx4 v128, s[48:49]
	s_add_i32 m0, s8, 0x2000
	s_nop 0
	global_load_lds_dwordx4 v130, s[48:49]
	s_mov_b32 m0, s65
	s_nop 0
	global_load_lds_dwordx4 v134, s[46:47]
	s_mov_b32 m0, s66
	s_nop 0
	global_load_lds_dwordx4 v132, s[46:47]
	s_waitcnt vmcnt(8)
	s_waitcnt lgkmcnt(0)
	s_barrier
	s_setprio 1
	s_waitcnt lgkmcnt(0)
	v_mfma_f32_16x16x32_bf16 v[60:63], v[166:169], v[198:201], v[60:63]
	v_mfma_f32_16x16x32_bf16 v[56:59], v[174:177], v[198:201], v[56:59]
	v_mfma_f32_16x16x32_bf16 v[44:47], v[166:169], v[206:209], v[44:47]
	v_mfma_f32_16x16x32_bf16 v[40:43], v[174:177], v[206:209], v[40:43]
	v_mfma_f32_16x16x32_bf16 v[28:31], v[166:169], v[214:217], v[28:31]
	v_mfma_f32_16x16x32_bf16 v[24:27], v[174:177], v[214:217], v[24:27]
	v_mfma_f32_16x16x32_bf16 v[12:15], v[166:169], v[222:225], v[12:15]
	v_mfma_f32_16x16x32_bf16 v[8:11], v[174:177], v[222:225], v[8:11]
	v_mfma_f32_16x16x32_bf16 v[60:63], v[170:173], v[202:205], v[60:63]
	v_mfma_f32_16x16x32_bf16 v[56:59], v[178:181], v[202:205], v[56:59]
	v_mfma_f32_16x16x32_bf16 v[44:47], v[170:173], v[210:213], v[44:47]
	v_mfma_f32_16x16x32_bf16 v[40:43], v[178:181], v[210:213], v[40:43]
	v_mfma_f32_16x16x32_bf16 v[28:31], v[170:173], v[218:221], v[28:31]
	v_mfma_f32_16x16x32_bf16 v[24:27], v[178:181], v[218:221], v[24:27]
	v_mfma_f32_16x16x32_bf16 v[12:15], v[170:173], v[226:229], v[12:15]
	v_mfma_f32_16x16x32_bf16 v[8:11], v[178:181], v[226:229], v[8:11]
	s_setprio 0
	s_setprio 1
	v_mfma_f32_16x16x32_bf16 v[52:55], v[182:185], v[198:201], v[52:55]
	v_mfma_f32_16x16x32_bf16 v[48:51], v[190:193], v[198:201], v[48:51]
	v_mfma_f32_16x16x32_bf16 v[36:39], v[182:185], v[206:209], v[36:39]
	v_mfma_f32_16x16x32_bf16 v[32:35], v[190:193], v[206:209], v[32:35]
	v_mfma_f32_16x16x32_bf16 v[20:23], v[182:185], v[214:217], v[20:23]
	v_mfma_f32_16x16x32_bf16 v[16:19], v[190:193], v[214:217], v[16:19]
	v_mfma_f32_16x16x32_bf16 v[4:7], v[182:185], v[222:225], v[4:7]
	v_mfma_f32_16x16x32_bf16 v[0:3], v[190:193], v[222:225], v[0:3]
	v_mfma_f32_16x16x32_bf16 v[52:55], v[186:189], v[202:205], v[52:55]
	v_mfma_f32_16x16x32_bf16 v[48:51], v[194:197], v[202:205], v[48:51]
	v_mfma_f32_16x16x32_bf16 v[36:39], v[186:189], v[210:213], v[36:39]
	v_mfma_f32_16x16x32_bf16 v[32:35], v[194:197], v[210:213], v[32:35]
	v_mfma_f32_16x16x32_bf16 v[20:23], v[186:189], v[218:221], v[20:23]
	v_mfma_f32_16x16x32_bf16 v[16:19], v[194:197], v[218:221], v[16:19]
	v_mfma_f32_16x16x32_bf16 v[4:7], v[186:189], v[226:229], v[4:7]
	v_mfma_f32_16x16x32_bf16 v[0:3], v[194:197], v[226:229], v[0:3]
	s_setprio 0
	s_barrier
	s_add_i32 s8, s81, 2
	s_add_u32 s44, s44, 0x100
	s_addc_u32 s45, s45, 0
	s_cmp_gt_u32 s81, 13
	s_mov_b32 s81, s8
	s_cbranch_scc1 .LBB0_813
	s_branch .LBB0_807

.LBB0_895:
	s_add_u32 s70, s55, s28
	s_addc_u32 s71, s56, s29
	s_add_u32 s72, s57, s30
	s_addc_u32 s73, s58, s31
	s_add_u32 s28, s4, 0x80
	s_addc_u32 s29, s5, 0
	s_add_u32 s30, s20, 0x80
	s_addc_u32 s31, s21, 0
	v_lshl_add_u64 v[128:129], s[26:27], 0, v[148:149]
	v_lshl_add_u64 v[130:131], s[26:27], 0, v[150:151]
	s_mov_b32 s78, 0
	s_mov_b64 s[36:37], 0
	s_cmpk_eq_i32 s36, 0x1500
	s_cselect_b64 s[44:45], -1, 0
	s_add_u32 s46, s26, s36
	s_addc_u32 s47, s27, s37
	s_add_u32 s80, s24, s36
	s_addc_u32 s79, s25, s37
	s_add_u32 s38, s46, 0x180
	s_addc_u32 s39, s47, 0
	s_add_u32 s40, s80, 0x180
	s_addc_u32 s41, s79, 0
	s_cmpk_eq_i32 s36, 0x1500
	s_cselect_b32 s38, s28, s38
	s_cselect_b32 s39, s29, s39
	s_cselect_b32 s40, s30, s40
	s_cselect_b32 s41, s31, s41
	v_add_u32_e32 v167, s64, v165
	ds_read_b128 v[132:135], v167
	ds_read_b128 v[156:159], v167 offset:1024
	ds_read_b128 v[160:163], v167 offset:2048
	ds_read_b128 v[168:171], v167 offset:3072
	v_add_u32_e32 v167, s65, v165
	ds_read_b128 v[172:175], v167
	ds_read_b128 v[176:179], v167 offset:1024
	ds_read_b128 v[180:183], v167 offset:2048
	ds_read_b128 v[184:187], v167 offset:3072
	s_add_u32 s8, s46, 0x100
	s_addc_u32 s81, s47, 0
	s_and_b64 s[46:47], exec, s[44:45]
	s_cselect_b32 s47, s5, s81
	s_cselect_b32 s46, s4, s8
	s_add_u32 s8, s80, 0x100
	s_addc_u32 s79, s79, 0
	s_and_b64 s[44:45], exec, s[44:45]
	s_cselect_b32 s45, s21, s79
	s_cselect_b32 s44, s20, s8
	v_lshl_add_u64 v[220:221], v[128:129], 0, s[36:37]
	s_add_i32 m0, s51, 0xc000
	ds_read_b128 v[188:191], v166
	ds_read_b128 v[192:195], v166 offset:1024
	ds_read_b128 v[196:199], v166 offset:2048
	ds_read_b128 v[200:203], v166 offset:3072
	ds_read_b128 v[204:207], v166 offset:4096
	ds_read_b128 v[208:211], v166 offset:5120
	ds_read_b128 v[212:215], v166 offset:6144
	ds_read_b128 v[216:219], v166 offset:7168
	global_load_lds_dwordx4 v[220:221], off
	v_lshl_add_u64 v[220:221], v[130:131], 0, s[36:37]
	s_add_i32 m0, s51, 0xe000
	s_nop 0
	global_load_lds_dwordx4 v[220:221], off
	s_waitcnt vmcnt(8)
	s_waitcnt lgkmcnt(0)
	s_barrier
	s_setprio 1
	s_waitcnt lgkmcnt(0)
	v_mfma_f32_16x16x32_bf16 v[124:127], v[132:135], v[188:191], 0
	v_mfma_f32_16x16x32_bf16 v[120:123], v[160:163], v[188:191], 0
	v_mfma_f32_16x16x32_bf16 v[108:111], v[132:135], v[196:199], 0
	v_mfma_f32_16x16x32_bf16 v[104:107], v[160:163], v[196:199], 0
	v_mfma_f32_16x16x32_bf16 v[92:95], v[132:135], v[204:207], 0
	v_mfma_f32_16x16x32_bf16 v[88:91], v[160:163], v[204:207], 0
	v_mfma_f32_16x16x32_bf16 v[76:79], v[132:135], v[212:215], 0
	v_mfma_f32_16x16x32_bf16 v[72:75], v[160:163], v[212:215], 0
	v_mfma_f32_16x16x32_bf16 v[124:127], v[156:159], v[192:195], v[124:127]
	v_mfma_f32_16x16x32_bf16 v[120:123], v[168:171], v[192:195], v[120:123]
	v_mfma_f32_16x16x32_bf16 v[108:111], v[156:159], v[200:203], v[108:111]
	v_mfma_f32_16x16x32_bf16 v[104:107], v[168:171], v[200:203], v[104:107]
	v_mfma_f32_16x16x32_bf16 v[92:95], v[156:159], v[208:211], v[92:95]
	v_mfma_f32_16x16x32_bf16 v[88:91], v[168:171], v[208:211], v[88:91]
	v_mfma_f32_16x16x32_bf16 v[76:79], v[156:159], v[216:219], v[76:79]
	v_mfma_f32_16x16x32_bf16 v[72:75], v[168:171], v[216:219], v[72:75]
	s_setprio 0
	s_setprio 1
	v_mfma_f32_16x16x32_bf16 v[116:119], v[172:175], v[188:191], 0
	v_mfma_f32_16x16x32_bf16 v[112:115], v[180:183], v[188:191], 0
	v_mfma_f32_16x16x32_bf16 v[100:103], v[172:175], v[196:199], 0
	v_mfma_f32_16x16x32_bf16 v[96:99], v[180:183], v[196:199], 0
	v_mfma_f32_16x16x32_bf16 v[84:87], v[172:175], v[204:207], 0
	v_mfma_f32_16x16x32_bf16 v[80:83], v[180:183], v[204:207], 0
	v_mfma_f32_16x16x32_bf16 v[68:71], v[172:175], v[212:215], 0
	v_mfma_f32_16x16x32_bf16 v[64:67], v[180:183], v[212:215], 0
	v_mfma_f32_16x16x32_bf16 v[116:119], v[176:179], v[192:195], v[116:119]
	v_mfma_f32_16x16x32_bf16 v[112:115], v[184:187], v[192:195], v[112:115]
	v_mfma_f32_16x16x32_bf16 v[100:103], v[176:179], v[200:203], v[100:103]
	v_mfma_f32_16x16x32_bf16 v[96:99], v[184:187], v[200:203], v[96:99]
	v_mfma_f32_16x16x32_bf16 v[84:87], v[176:179], v[208:211], v[84:87]
	v_mfma_f32_16x16x32_bf16 v[80:83], v[184:187], v[208:211], v[80:83]
	v_mfma_f32_16x16x32_bf16 v[68:71], v[176:179], v[216:219], v[68:71]
	v_mfma_f32_16x16x32_bf16 v[64:67], v[184:187], v[216:219], v[64:67]
	s_setprio 0
	s_barrier
	s_add_i32 s8, s64, s50
	s_mov_b32 m0, s8
	ds_read_b128 v[188:191], v166 offset:16384
	ds_read_b128 v[192:195], v166 offset:17408
	ds_read_b128 v[196:199], v166 offset:18432
	ds_read_b128 v[200:203], v166 offset:19456
	ds_read_b128 v[204:207], v166 offset:20480
	ds_read_b128 v[208:211], v166 offset:21504
	ds_read_b128 v[212:215], v166 offset:22528
	ds_read_b128 v[216:219], v166 offset:23552
	global_load_lds_dwordx4 v138, s[44:45]
	s_add_i32 m0, s8, 0x2000
	s_nop 0
	global_load_lds_dwordx4 v142, s[44:45]
	s_add_u32 s44, s44, 0xb0000
	s_addc_u32 s45, s45, 0
	s_add_i32 s8, s65, s50
	s_mov_b32 m0, s8
	s_nop 0
	global_load_lds_dwordx4 v138, s[44:45]
	s_add_i32 m0, s8, 0x2000
	s_nop 0
	global_load_lds_dwordx4 v142, s[44:45]
	s_mov_b32 m0, s51
	s_nop 0
	global_load_lds_dwordx4 v136, s[46:47]
	s_mov_b32 m0, s52
	s_nop 0
	global_load_lds_dwordx4 v140, s[46:47]
	s_waitcnt vmcnt(8)
	s_waitcnt lgkmcnt(0)
	s_barrier
	s_setprio 1
	s_waitcnt lgkmcnt(0)
	v_mfma_f32_16x16x32_bf16 v[60:63], v[132:135], v[188:191], 0
	v_mfma_f32_16x16x32_bf16 v[56:59], v[160:163], v[188:191], 0
	v_mfma_f32_16x16x32_bf16 v[44:47], v[132:135], v[196:199], 0
	v_mfma_f32_16x16x32_bf16 v[40:43], v[160:163], v[196:199], 0
	v_mfma_f32_16x16x32_bf16 v[28:31], v[132:135], v[204:207], 0
	v_mfma_f32_16x16x32_bf16 v[24:27], v[160:163], v[204:207], 0
	v_mfma_f32_16x16x32_bf16 v[12:15], v[132:135], v[212:215], 0
	v_mfma_f32_16x16x32_bf16 v[8:11], v[160:163], v[212:215], 0
	v_mfma_f32_16x16x32_bf16 v[60:63], v[156:159], v[192:195], v[60:63]
	v_mfma_f32_16x16x32_bf16 v[56:59], v[168:171], v[192:195], v[56:59]
	v_mfma_f32_16x16x32_bf16 v[44:47], v[156:159], v[200:203], v[44:47]
	v_mfma_f32_16x16x32_bf16 v[40:43], v[168:171], v[200:203], v[40:43]
	v_mfma_f32_16x16x32_bf16 v[28:31], v[156:159], v[208:211], v[28:31]
	v_mfma_f32_16x16x32_bf16 v[24:27], v[168:171], v[208:211], v[24:27]
	v_mfma_f32_16x16x32_bf16 v[12:15], v[156:159], v[216:219], v[12:15]
	v_mfma_f32_16x16x32_bf16 v[8:11], v[168:171], v[216:219], v[8:11]
	s_setprio 0
	s_setprio 1
	v_mfma_f32_16x16x32_bf16 v[52:55], v[172:175], v[188:191], 0
	v_mfma_f32_16x16x32_bf16 v[48:51], v[180:183], v[188:191], 0
	v_mfma_f32_16x16x32_bf16 v[36:39], v[172:175], v[196:199], 0
	v_mfma_f32_16x16x32_bf16 v[32:35], v[180:183], v[196:199], 0
	v_mfma_f32_16x16x32_bf16 v[20:23], v[172:175], v[204:207], 0
	v_mfma_f32_16x16x32_bf16 v[16:19], v[180:183], v[204:207], 0
	v_mfma_f32_16x16x32_bf16 v[4:7], v[172:175], v[212:215], 0
	v_mfma_f32_16x16x32_bf16 v[0:3], v[180:183], v[212:215], 0
	v_mfma_f32_16x16x32_bf16 v[52:55], v[176:179], v[192:195], v[52:55]
	v_mfma_f32_16x16x32_bf16 v[48:51], v[184:187], v[192:195], v[48:51]
	v_mfma_f32_16x16x32_bf16 v[36:39], v[176:179], v[200:203], v[36:39]
	v_mfma_f32_16x16x32_bf16 v[32:35], v[184:187], v[200:203], v[32:35]
	v_mfma_f32_16x16x32_bf16 v[20:23], v[176:179], v[208:211], v[20:23]
	v_mfma_f32_16x16x32_bf16 v[16:19], v[184:187], v[208:211], v[16:19]
	v_mfma_f32_16x16x32_bf16 v[4:7], v[176:179], v[216:219], v[4:7]
	v_mfma_f32_16x16x32_bf16 v[0:3], v[184:187], v[216:219], v[0:3]
	s_setprio 0
	s_barrier
	s_add_i32 s8, 0, 0x18000
	v_add_u32_e32 v167, s8, v165
	s_add_i32 s79, 0, 0x1c000
	ds_read_b128 v[132:135], v167
	ds_read_b128 v[156:159], v167 offset:1024
	ds_read_b128 v[160:163], v167 offset:2048
	ds_read_b128 v[168:171], v167 offset:3072
	v_add_u32_e32 v167, s79, v165
	ds_read_b128 v[172:175], v167
	ds_read_b128 v[176:179], v167 offset:1024
	ds_read_b128 v[180:183], v167 offset:2048
	ds_read_b128 v[184:187], v167 offset:3072
	s_add_u32 s44, s46, 0xb0000
	s_addc_u32 s45, s47, 0
	s_mov_b32 m0, s53
	ds_read_b128 v[188:191], v166 offset:32768
	ds_read_b128 v[192:195], v166 offset:33792
	ds_read_b128 v[196:199], v166 offset:34816
	ds_read_b128 v[200:203], v166 offset:35840
	ds_read_b128 v[204:207], v166 offset:36864
	ds_read_b128 v[208:211], v166 offset:37888
	ds_read_b128 v[212:215], v166 offset:38912
	ds_read_b128 v[216:219], v166 offset:39936
	global_load_lds_dwordx4 v136, s[44:45]
	s_mov_b32 m0, s54
	s_nop 0
	global_load_lds_dwordx4 v140, s[44:45]
	s_waitcnt vmcnt(8)
	s_waitcnt lgkmcnt(0)
	s_barrier
	s_setprio 1
	s_waitcnt lgkmcnt(0)
	v_mfma_f32_16x16x32_bf16 v[124:127], v[132:135], v[188:191], v[124:127]
	v_mfma_f32_16x16x32_bf16 v[120:123], v[160:163], v[188:191], v[120:123]
	v_mfma_f32_16x16x32_bf16 v[108:111], v[132:135], v[196:199], v[108:111]
	v_mfma_f32_16x16x32_bf16 v[104:107], v[160:163], v[196:199], v[104:107]
	v_mfma_f32_16x16x32_bf16 v[92:95], v[132:135], v[204:207], v[92:95]
	v_mfma_f32_16x16x32_bf16 v[88:91], v[160:163], v[204:207], v[88:91]
	v_mfma_f32_16x16x32_bf16 v[76:79], v[132:135], v[212:215], v[76:79]
	v_mfma_f32_16x16x32_bf16 v[72:75], v[160:163], v[212:215], v[72:75]
	v_mfma_f32_16x16x32_bf16 v[124:127], v[156:159], v[192:195], v[124:127]
	v_mfma_f32_16x16x32_bf16 v[120:123], v[168:171], v[192:195], v[120:123]
	v_mfma_f32_16x16x32_bf16 v[108:111], v[156:159], v[200:203], v[108:111]
	v_mfma_f32_16x16x32_bf16 v[104:107], v[168:171], v[200:203], v[104:107]
	v_mfma_f32_16x16x32_bf16 v[92:95], v[156:159], v[208:211], v[92:95]
	v_mfma_f32_16x16x32_bf16 v[88:91], v[168:171], v[208:211], v[88:91]
	v_mfma_f32_16x16x32_bf16 v[76:79], v[156:159], v[216:219], v[76:79]
	v_mfma_f32_16x16x32_bf16 v[72:75], v[168:171], v[216:219], v[72:75]
	s_setprio 0
	s_setprio 1
	v_mfma_f32_16x16x32_bf16 v[116:119], v[172:175], v[188:191], v[116:119]
	v_mfma_f32_16x16x32_bf16 v[112:115], v[180:183], v[188:191], v[112:115]
	v_mfma_f32_16x16x32_bf16 v[100:103], v[172:175], v[196:199], v[100:103]
	v_mfma_f32_16x16x32_bf16 v[96:99], v[180:183], v[196:199], v[96:99]
	v_mfma_f32_16x16x32_bf16 v[84:87], v[172:175], v[204:207], v[84:87]
	v_mfma_f32_16x16x32_bf16 v[80:83], v[180:183], v[204:207], v[80:83]
	v_mfma_f32_16x16x32_bf16 v[68:71], v[172:175], v[212:215], v[68:71]
	v_mfma_f32_16x16x32_bf16 v[64:67], v[180:183], v[212:215], v[64:67]
	v_mfma_f32_16x16x32_bf16 v[116:119], v[176:179], v[192:195], v[116:119]
	v_mfma_f32_16x16x32_bf16 v[112:115], v[184:187], v[192:195], v[112:115]
	v_mfma_f32_16x16x32_bf16 v[100:103], v[176:179], v[200:203], v[100:103]
	v_mfma_f32_16x16x32_bf16 v[96:99], v[184:187], v[200:203], v[96:99]
	v_mfma_f32_16x16x32_bf16 v[84:87], v[176:179], v[208:211], v[84:87]
	v_mfma_f32_16x16x32_bf16 v[80:83], v[184:187], v[208:211], v[80:83]
	v_mfma_f32_16x16x32_bf16 v[68:71], v[176:179], v[216:219], v[68:71]
	v_mfma_f32_16x16x32_bf16 v[64:67], v[184:187], v[216:219], v[64:67]
	s_setprio 0
	s_barrier
	s_add_i32 s8, s8, s50
	s_mov_b32 m0, s8
	ds_read_b128 v[188:191], v166 offset:49152
	ds_read_b128 v[192:195], v166 offset:50176
	ds_read_b128 v[196:199], v166 offset:51200
	ds_read_b128 v[200:203], v166 offset:52224
	ds_read_b128 v[204:207], v166 offset:53248
	ds_read_b128 v[208:211], v166 offset:54272
	ds_read_b128 v[212:215], v166 offset:55296
	ds_read_b128 v[216:219], v166 offset:56320
	global_load_lds_dwordx4 v138, s[40:41]
	s_add_i32 m0, s8, 0x2000
	s_nop 0
	global_load_lds_dwordx4 v142, s[40:41]
	s_add_u32 s40, s40, 0xb0000
	s_addc_u32 s41, s41, 0
	s_add_i32 s8, s79, s50
	s_mov_b32 m0, s8
	s_nop 0
	global_load_lds_dwordx4 v138, s[40:41]
	s_add_i32 m0, s8, 0x2000
	s_nop 0
	global_load_lds_dwordx4 v142, s[40:41]
	s_mov_b32 m0, s60
	s_nop 0
	global_load_lds_dwordx4 v136, s[38:39]
	s_mov_b32 m0, s61
	s_nop 0
	global_load_lds_dwordx4 v140, s[38:39]
	s_waitcnt vmcnt(8)
	s_waitcnt lgkmcnt(0)
	s_barrier
	s_setprio 1
	s_waitcnt lgkmcnt(0)
	v_mfma_f32_16x16x32_bf16 v[60:63], v[132:135], v[188:191], v[60:63]
	v_mfma_f32_16x16x32_bf16 v[56:59], v[160:163], v[188:191], v[56:59]
	v_mfma_f32_16x16x32_bf16 v[44:47], v[132:135], v[196:199], v[44:47]
	v_mfma_f32_16x16x32_bf16 v[40:43], v[160:163], v[196:199], v[40:43]
	v_mfma_f32_16x16x32_bf16 v[28:31], v[132:135], v[204:207], v[28:31]
	v_mfma_f32_16x16x32_bf16 v[24:27], v[160:163], v[204:207], v[24:27]
	v_mfma_f32_16x16x32_bf16 v[12:15], v[132:135], v[212:215], v[12:15]
	v_mfma_f32_16x16x32_bf16 v[8:11], v[160:163], v[212:215], v[8:11]
	v_mfma_f32_16x16x32_bf16 v[60:63], v[156:159], v[192:195], v[60:63]
	v_mfma_f32_16x16x32_bf16 v[56:59], v[168:171], v[192:195], v[56:59]
	v_mfma_f32_16x16x32_bf16 v[44:47], v[156:159], v[200:203], v[44:47]
	v_mfma_f32_16x16x32_bf16 v[40:43], v[168:171], v[200:203], v[40:43]
	v_mfma_f32_16x16x32_bf16 v[28:31], v[156:159], v[208:211], v[28:31]
	v_mfma_f32_16x16x32_bf16 v[24:27], v[168:171], v[208:211], v[24:27]
	v_mfma_f32_16x16x32_bf16 v[12:15], v[156:159], v[216:219], v[12:15]
	v_mfma_f32_16x16x32_bf16 v[8:11], v[168:171], v[216:219], v[8:11]
	s_setprio 0
	s_setprio 1
	v_mfma_f32_16x16x32_bf16 v[52:55], v[172:175], v[188:191], v[52:55]
	v_mfma_f32_16x16x32_bf16 v[48:51], v[180:183], v[188:191], v[48:51]
	v_mfma_f32_16x16x32_bf16 v[36:39], v[172:175], v[196:199], v[36:39]
	v_mfma_f32_16x16x32_bf16 v[32:35], v[180:183], v[196:199], v[32:35]
	v_mfma_f32_16x16x32_bf16 v[20:23], v[172:175], v[204:207], v[20:23]
	v_mfma_f32_16x16x32_bf16 v[16:19], v[180:183], v[204:207], v[16:19]
	v_mfma_f32_16x16x32_bf16 v[4:7], v[172:175], v[212:215], v[4:7]
	v_mfma_f32_16x16x32_bf16 v[0:3], v[180:183], v[212:215], v[0:3]
	v_mfma_f32_16x16x32_bf16 v[52:55], v[176:179], v[192:195], v[52:55]
	v_mfma_f32_16x16x32_bf16 v[48:51], v[184:187], v[192:195], v[48:51]
	v_mfma_f32_16x16x32_bf16 v[36:39], v[176:179], v[200:203], v[36:39]
	v_mfma_f32_16x16x32_bf16 v[32:35], v[184:187], v[200:203], v[32:35]
	v_mfma_f32_16x16x32_bf16 v[20:23], v[176:179], v[208:211], v[20:23]
	v_mfma_f32_16x16x32_bf16 v[16:19], v[184:187], v[208:211], v[16:19]
	v_mfma_f32_16x16x32_bf16 v[4:7], v[176:179], v[216:219], v[4:7]
	v_mfma_f32_16x16x32_bf16 v[0:3], v[184:187], v[216:219], v[0:3]
	s_setprio 0
	s_barrier
	s_add_i32 s8, s78, 2
	s_add_u32 s36, s36, 0x100
	s_addc_u32 s37, s37, 0
	s_cmp_gt_u32 s78, 41
	s_mov_b32 s78, s8
	s_cbranch_scc1 .LBB0_903
	s_branch .LBB0_897

.LBB0_1017:
	s_add_u32 s65, s54, s6
	s_addc_u32 s66, s55, s7
	s_add_u32 s67, s56, s8
	s_addc_u32 s68, s57, s9
	s_ashr_i32 s19, s18, 31
	s_lshl_b64 s[6:7], s[18:19], 19
	s_add_u32 s20, s34, s6
	s_addc_u32 s21, s35, s7
	s_and_b64 s[8:9], s[0:1], exec
	s_cselect_b32 s19, s21, s29
	s_cselect_b32 s69, s20, s28
	s_ashr_i32 s17, s16, 31
	s_lshl_b64 s[8:9], s[16:17], 19
	s_add_u32 s22, s48, s8
	s_addc_u32 s23, s49, s9
	s_and_b64 s[30:31], s[0:1], exec
	s_cselect_b32 s17, s23, s27
	s_cselect_b32 s70, s22, s26
	s_add_u32 s30, s69, 0x80
	s_addc_u32 s31, s19, 0
	s_add_u32 s36, s70, 0x80
	s_addc_u32 s37, s17, 0
	v_lshl_add_u64 v[128:129], s[28:29], 0, v[196:197]
	v_lshl_add_u64 v[130:131], s[28:29], 0, v[198:199]
	s_mov_b32 s71, 0
	s_mov_b64 s[38:39], 0
	s_cmpk_eq_i32 s38, 0x700
	s_cselect_b64 s[44:45], -1, 0
	s_add_u32 s46, s28, s38
	s_addc_u32 s47, s29, s39
	s_add_u32 s73, s26, s38
	s_addc_u32 s72, s27, s39
	s_add_u32 s40, s46, 0x180
	s_addc_u32 s41, s47, 0
	s_add_u32 s42, s73, 0x180
	s_addc_u32 s43, s72, 0
	s_cmpk_eq_i32 s38, 0x700
	s_cselect_b32 s40, s30, s40
	s_cselect_b32 s41, s31, s41
	s_cselect_b32 s42, s36, s42
	s_cselect_b32 s43, s37, s43
	v_add_u32_e32 v144, s61, v220
	v_add_u32_e32 v160, s62, v220
	ds_read_b128 v[132:135], v144
	ds_read_b128 v[136:139], v144 offset:1024
	ds_read_b128 v[140:143], v144 offset:2048
	ds_read_b128 v[144:147], v144 offset:3072
	ds_read_b128 v[148:151], v160
	ds_read_b128 v[152:155], v160 offset:1024
	ds_read_b128 v[156:159], v160 offset:2048
	ds_read_b128 v[160:163], v160 offset:3072
	s_add_u32 s10, s46, 0x100
	s_addc_u32 s76, s47, 0
	s_and_b64 s[46:47], exec, s[44:45]
	s_cselect_b32 s47, s19, s76
	s_cselect_b32 s46, s69, s10
	s_add_u32 s10, s73, 0x100
	s_addc_u32 s72, s72, 0
	s_and_b64 s[44:45], exec, s[44:45]
	s_cselect_b32 s45, s17, s72
	s_cselect_b32 s44, s70, s10
	v_lshl_add_u64 v[216:217], v[128:129], 0, s[38:39]
	s_add_i32 m0, s25, 0xc000
	ds_read_b128 v[164:167], v221
	ds_read_b128 v[168:171], v221 offset:1024
	ds_read_b128 v[172:175], v221 offset:2048
	ds_read_b128 v[176:179], v221 offset:3072
	ds_read_b128 v[180:183], v221 offset:4096
	ds_read_b128 v[204:207], v221 offset:5120
	ds_read_b128 v[208:211], v221 offset:6144
	ds_read_b128 v[212:215], v221 offset:7168
	global_load_lds_dwordx4 v[216:217], off
	v_lshl_add_u64 v[216:217], v[130:131], 0, s[38:39]
	s_add_i32 m0, s25, 0xe000
	s_nop 0
	global_load_lds_dwordx4 v[216:217], off
	s_waitcnt vmcnt(8)
	s_waitcnt lgkmcnt(0)
	s_barrier
	s_setprio 1
	s_waitcnt lgkmcnt(0)
	v_mfma_f32_16x16x32_bf16 v[124:127], v[132:135], v[164:167], 0
	v_mfma_f32_16x16x32_bf16 v[120:123], v[140:143], v[164:167], 0
	v_mfma_f32_16x16x32_bf16 v[108:111], v[132:135], v[172:175], 0
	v_mfma_f32_16x16x32_bf16 v[104:107], v[140:143], v[172:175], 0
	v_mfma_f32_16x16x32_bf16 v[92:95], v[132:135], v[180:183], 0
	v_mfma_f32_16x16x32_bf16 v[88:91], v[140:143], v[180:183], 0
	v_mfma_f32_16x16x32_bf16 v[76:79], v[132:135], v[208:211], 0
	v_mfma_f32_16x16x32_bf16 v[72:75], v[140:143], v[208:211], 0
	v_mfma_f32_16x16x32_bf16 v[124:127], v[136:139], v[168:171], v[124:127]
	v_mfma_f32_16x16x32_bf16 v[120:123], v[144:147], v[168:171], v[120:123]
	v_mfma_f32_16x16x32_bf16 v[108:111], v[136:139], v[176:179], v[108:111]
	v_mfma_f32_16x16x32_bf16 v[104:107], v[144:147], v[176:179], v[104:107]
	v_mfma_f32_16x16x32_bf16 v[92:95], v[136:139], v[204:207], v[92:95]
	v_mfma_f32_16x16x32_bf16 v[88:91], v[144:147], v[204:207], v[88:91]
	v_mfma_f32_16x16x32_bf16 v[76:79], v[136:139], v[212:215], v[76:79]
	v_mfma_f32_16x16x32_bf16 v[72:75], v[144:147], v[212:215], v[72:75]
	s_setprio 0
	s_setprio 1
	v_mfma_f32_16x16x32_bf16 v[116:119], v[148:151], v[164:167], 0
	v_mfma_f32_16x16x32_bf16 v[112:115], v[156:159], v[164:167], 0
	v_mfma_f32_16x16x32_bf16 v[100:103], v[148:151], v[172:175], 0
	v_mfma_f32_16x16x32_bf16 v[96:99], v[156:159], v[172:175], 0
	v_mfma_f32_16x16x32_bf16 v[84:87], v[148:151], v[180:183], 0
	v_mfma_f32_16x16x32_bf16 v[80:83], v[156:159], v[180:183], 0
	v_mfma_f32_16x16x32_bf16 v[68:71], v[148:151], v[208:211], 0
	v_mfma_f32_16x16x32_bf16 v[64:67], v[156:159], v[208:211], 0
	v_mfma_f32_16x16x32_bf16 v[116:119], v[152:155], v[168:171], v[116:119]
	v_mfma_f32_16x16x32_bf16 v[112:115], v[160:163], v[168:171], v[112:115]
	v_mfma_f32_16x16x32_bf16 v[100:103], v[152:155], v[176:179], v[100:103]
	v_mfma_f32_16x16x32_bf16 v[96:99], v[160:163], v[176:179], v[96:99]
	v_mfma_f32_16x16x32_bf16 v[84:87], v[152:155], v[204:207], v[84:87]
	v_mfma_f32_16x16x32_bf16 v[80:83], v[160:163], v[204:207], v[80:83]
	v_mfma_f32_16x16x32_bf16 v[68:71], v[152:155], v[212:215], v[68:71]
	v_mfma_f32_16x16x32_bf16 v[64:67], v[160:163], v[212:215], v[64:67]
	s_setprio 0
	s_barrier
	s_add_i32 s10, s61, s50
	s_mov_b32 m0, s10
	ds_read_b128 v[164:167], v221 offset:16384
	ds_read_b128 v[168:171], v221 offset:17408
	ds_read_b128 v[172:175], v221 offset:18432
	ds_read_b128 v[176:179], v221 offset:19456
	ds_read_b128 v[180:183], v221 offset:20480
	ds_read_b128 v[204:207], v221 offset:21504
	ds_read_b128 v[208:211], v221 offset:22528
	ds_read_b128 v[212:215], v221 offset:23552
	global_load_lds_dwordx4 v186, s[44:45]
	s_add_i32 m0, s10, 0x2000
	s_nop 0
	global_load_lds_dwordx4 v190, s[44:45]
	s_add_u32 s44, s44, 0x40000
	s_addc_u32 s45, s45, 0
	s_add_i32 s10, s62, s50
	s_mov_b32 m0, s10
	s_nop 0
	global_load_lds_dwordx4 v186, s[44:45]
	s_add_i32 m0, s10, 0x2000
	s_nop 0
	global_load_lds_dwordx4 v190, s[44:45]
	s_mov_b32 m0, s25
	s_nop 0
	global_load_lds_dwordx4 v184, s[46:47]
	s_mov_b32 m0, s51
	s_nop 0
	global_load_lds_dwordx4 v188, s[46:47]
	s_waitcnt vmcnt(8)
	s_waitcnt lgkmcnt(0)
	s_barrier
	s_setprio 1
	s_waitcnt lgkmcnt(0)
	v_mfma_f32_16x16x32_bf16 v[60:63], v[132:135], v[164:167], 0
	v_mfma_f32_16x16x32_bf16 v[56:59], v[140:143], v[164:167], 0
	v_mfma_f32_16x16x32_bf16 v[44:47], v[132:135], v[172:175], 0
	v_mfma_f32_16x16x32_bf16 v[40:43], v[140:143], v[172:175], 0
	v_mfma_f32_16x16x32_bf16 v[28:31], v[132:135], v[180:183], 0
	v_mfma_f32_16x16x32_bf16 v[24:27], v[140:143], v[180:183], 0
	v_mfma_f32_16x16x32_bf16 v[12:15], v[132:135], v[208:211], 0
	v_mfma_f32_16x16x32_bf16 v[8:11], v[140:143], v[208:211], 0
	v_mfma_f32_16x16x32_bf16 v[60:63], v[136:139], v[168:171], v[60:63]
	v_mfma_f32_16x16x32_bf16 v[56:59], v[144:147], v[168:171], v[56:59]
	v_mfma_f32_16x16x32_bf16 v[44:47], v[136:139], v[176:179], v[44:47]
	v_mfma_f32_16x16x32_bf16 v[40:43], v[144:147], v[176:179], v[40:43]
	v_mfma_f32_16x16x32_bf16 v[28:31], v[136:139], v[204:207], v[28:31]
	v_mfma_f32_16x16x32_bf16 v[24:27], v[144:147], v[204:207], v[24:27]
	v_mfma_f32_16x16x32_bf16 v[12:15], v[136:139], v[212:215], v[12:15]
	v_mfma_f32_16x16x32_bf16 v[8:11], v[144:147], v[212:215], v[8:11]
	s_setprio 0
	s_setprio 1
	v_mfma_f32_16x16x32_bf16 v[52:55], v[148:151], v[164:167], 0
	v_mfma_f32_16x16x32_bf16 v[48:51], v[156:159], v[164:167], 0
	v_mfma_f32_16x16x32_bf16 v[36:39], v[148:151], v[172:175], 0
	v_mfma_f32_16x16x32_bf16 v[32:35], v[156:159], v[172:175], 0
	v_mfma_f32_16x16x32_bf16 v[20:23], v[148:151], v[180:183], 0
	v_mfma_f32_16x16x32_bf16 v[16:19], v[156:159], v[180:183], 0
	v_mfma_f32_16x16x32_bf16 v[4:7], v[148:151], v[208:211], 0
	v_mfma_f32_16x16x32_bf16 v[0:3], v[156:159], v[208:211], 0
	v_mfma_f32_16x16x32_bf16 v[52:55], v[152:155], v[168:171], v[52:55]
	v_mfma_f32_16x16x32_bf16 v[48:51], v[160:163], v[168:171], v[48:51]
	v_mfma_f32_16x16x32_bf16 v[36:39], v[152:155], v[176:179], v[36:39]
	v_mfma_f32_16x16x32_bf16 v[32:35], v[160:163], v[176:179], v[32:35]
	v_mfma_f32_16x16x32_bf16 v[20:23], v[152:155], v[204:207], v[20:23]
	v_mfma_f32_16x16x32_bf16 v[16:19], v[160:163], v[204:207], v[16:19]
	v_mfma_f32_16x16x32_bf16 v[4:7], v[152:155], v[212:215], v[4:7]
	v_mfma_f32_16x16x32_bf16 v[0:3], v[160:163], v[212:215], v[0:3]
	s_setprio 0
	s_barrier
	s_add_i32 s10, 0, 0x18000
	s_add_i32 s72, 0, 0x1c000
	v_add_u32_e32 v144, s10, v220
	v_add_u32_e32 v160, s72, v220
	ds_read_b128 v[132:135], v144
	ds_read_b128 v[136:139], v144 offset:1024
	ds_read_b128 v[140:143], v144 offset:2048
	ds_read_b128 v[144:147], v144 offset:3072
	ds_read_b128 v[148:151], v160
	ds_read_b128 v[152:155], v160 offset:1024
	ds_read_b128 v[156:159], v160 offset:2048
	ds_read_b128 v[160:163], v160 offset:3072
	s_add_u32 s44, s46, 0x40000
	s_addc_u32 s45, s47, 0
	s_mov_b32 m0, s52
	ds_read_b128 v[164:167], v221 offset:32768
	ds_read_b128 v[168:171], v221 offset:33792
	ds_read_b128 v[172:175], v221 offset:34816
	ds_read_b128 v[176:179], v221 offset:35840
	ds_read_b128 v[180:183], v221 offset:36864
	ds_read_b128 v[204:207], v221 offset:37888
	ds_read_b128 v[208:211], v221 offset:38912
	ds_read_b128 v[212:215], v221 offset:39936
	global_load_lds_dwordx4 v184, s[44:45]
	s_mov_b32 m0, s53
	s_nop 0
	global_load_lds_dwordx4 v188, s[44:45]
	s_waitcnt vmcnt(8)
	s_waitcnt lgkmcnt(0)
	s_barrier
	s_setprio 1
	s_waitcnt lgkmcnt(0)
	v_mfma_f32_16x16x32_bf16 v[124:127], v[132:135], v[164:167], v[124:127]
	v_mfma_f32_16x16x32_bf16 v[120:123], v[140:143], v[164:167], v[120:123]
	v_mfma_f32_16x16x32_bf16 v[108:111], v[132:135], v[172:175], v[108:111]
	v_mfma_f32_16x16x32_bf16 v[104:107], v[140:143], v[172:175], v[104:107]
	v_mfma_f32_16x16x32_bf16 v[92:95], v[132:135], v[180:183], v[92:95]
	v_mfma_f32_16x16x32_bf16 v[88:91], v[140:143], v[180:183], v[88:91]
	v_mfma_f32_16x16x32_bf16 v[76:79], v[132:135], v[208:211], v[76:79]
	v_mfma_f32_16x16x32_bf16 v[72:75], v[140:143], v[208:211], v[72:75]
	v_mfma_f32_16x16x32_bf16 v[124:127], v[136:139], v[168:171], v[124:127]
	v_mfma_f32_16x16x32_bf16 v[120:123], v[144:147], v[168:171], v[120:123]
	v_mfma_f32_16x16x32_bf16 v[108:111], v[136:139], v[176:179], v[108:111]
	v_mfma_f32_16x16x32_bf16 v[104:107], v[144:147], v[176:179], v[104:107]
	v_mfma_f32_16x16x32_bf16 v[92:95], v[136:139], v[204:207], v[92:95]
	v_mfma_f32_16x16x32_bf16 v[88:91], v[144:147], v[204:207], v[88:91]
	v_mfma_f32_16x16x32_bf16 v[76:79], v[136:139], v[212:215], v[76:79]
	v_mfma_f32_16x16x32_bf16 v[72:75], v[144:147], v[212:215], v[72:75]
	s_setprio 0
	s_setprio 1
	v_mfma_f32_16x16x32_bf16 v[116:119], v[148:151], v[164:167], v[116:119]
	v_mfma_f32_16x16x32_bf16 v[112:115], v[156:159], v[164:167], v[112:115]
	v_mfma_f32_16x16x32_bf16 v[100:103], v[148:151], v[172:175], v[100:103]
	v_mfma_f32_16x16x32_bf16 v[96:99], v[156:159], v[172:175], v[96:99]
	v_mfma_f32_16x16x32_bf16 v[84:87], v[148:151], v[180:183], v[84:87]
	v_mfma_f32_16x16x32_bf16 v[80:83], v[156:159], v[180:183], v[80:83]
	v_mfma_f32_16x16x32_bf16 v[68:71], v[148:151], v[208:211], v[68:71]
	v_mfma_f32_16x16x32_bf16 v[64:67], v[156:159], v[208:211], v[64:67]
	v_mfma_f32_16x16x32_bf16 v[116:119], v[152:155], v[168:171], v[116:119]
	v_mfma_f32_16x16x32_bf16 v[112:115], v[160:163], v[168:171], v[112:115]
	v_mfma_f32_16x16x32_bf16 v[100:103], v[152:155], v[176:179], v[100:103]
	v_mfma_f32_16x16x32_bf16 v[96:99], v[160:163], v[176:179], v[96:99]
	v_mfma_f32_16x16x32_bf16 v[84:87], v[152:155], v[204:207], v[84:87]
	v_mfma_f32_16x16x32_bf16 v[80:83], v[160:163], v[204:207], v[80:83]
	v_mfma_f32_16x16x32_bf16 v[68:71], v[152:155], v[212:215], v[68:71]
	v_mfma_f32_16x16x32_bf16 v[64:67], v[160:163], v[212:215], v[64:67]
	s_setprio 0
	s_barrier
	s_add_i32 s10, s10, s50
	s_mov_b32 m0, s10
	ds_read_b128 v[164:167], v221 offset:49152
	ds_read_b128 v[168:171], v221 offset:50176
	ds_read_b128 v[172:175], v221 offset:51200
	ds_read_b128 v[176:179], v221 offset:52224
	ds_read_b128 v[180:183], v221 offset:53248
	ds_read_b128 v[204:207], v221 offset:54272
	ds_read_b128 v[208:211], v221 offset:55296
	ds_read_b128 v[212:215], v221 offset:56320
	global_load_lds_dwordx4 v186, s[42:43]
	s_add_i32 m0, s10, 0x2000
	s_nop 0
	global_load_lds_dwordx4 v190, s[42:43]
	s_add_u32 s42, s42, 0x40000
	s_addc_u32 s43, s43, 0
	s_add_i32 s10, s72, s50
	s_mov_b32 m0, s10
	s_nop 0
	global_load_lds_dwordx4 v186, s[42:43]
	s_add_i32 m0, s10, 0x2000
	s_nop 0
	global_load_lds_dwordx4 v190, s[42:43]
	s_mov_b32 m0, s58
	s_nop 0
	global_load_lds_dwordx4 v184, s[40:41]
	s_mov_b32 m0, s59
	s_nop 0
	global_load_lds_dwordx4 v188, s[40:41]
	s_waitcnt vmcnt(8)
	s_waitcnt lgkmcnt(0)
	s_barrier
	s_setprio 1
	s_waitcnt lgkmcnt(0)
	v_mfma_f32_16x16x32_bf16 v[60:63], v[132:135], v[164:167], v[60:63]
	v_mfma_f32_16x16x32_bf16 v[56:59], v[140:143], v[164:167], v[56:59]
	v_mfma_f32_16x16x32_bf16 v[44:47], v[132:135], v[172:175], v[44:47]
	v_mfma_f32_16x16x32_bf16 v[40:43], v[140:143], v[172:175], v[40:43]
	v_mfma_f32_16x16x32_bf16 v[28:31], v[132:135], v[180:183], v[28:31]
	v_mfma_f32_16x16x32_bf16 v[24:27], v[140:143], v[180:183], v[24:27]
	v_mfma_f32_16x16x32_bf16 v[12:15], v[132:135], v[208:211], v[12:15]
	v_mfma_f32_16x16x32_bf16 v[8:11], v[140:143], v[208:211], v[8:11]
	v_mfma_f32_16x16x32_bf16 v[60:63], v[136:139], v[168:171], v[60:63]
	v_mfma_f32_16x16x32_bf16 v[56:59], v[144:147], v[168:171], v[56:59]
	v_mfma_f32_16x16x32_bf16 v[44:47], v[136:139], v[176:179], v[44:47]
	v_mfma_f32_16x16x32_bf16 v[40:43], v[144:147], v[176:179], v[40:43]
	v_mfma_f32_16x16x32_bf16 v[28:31], v[136:139], v[204:207], v[28:31]
	v_mfma_f32_16x16x32_bf16 v[24:27], v[144:147], v[204:207], v[24:27]
	v_mfma_f32_16x16x32_bf16 v[12:15], v[136:139], v[212:215], v[12:15]
	v_mfma_f32_16x16x32_bf16 v[8:11], v[144:147], v[212:215], v[8:11]
	s_setprio 0
	s_setprio 1
	v_mfma_f32_16x16x32_bf16 v[52:55], v[148:151], v[164:167], v[52:55]
	v_mfma_f32_16x16x32_bf16 v[48:51], v[156:159], v[164:167], v[48:51]
	v_mfma_f32_16x16x32_bf16 v[36:39], v[148:151], v[172:175], v[36:39]
	v_mfma_f32_16x16x32_bf16 v[32:35], v[156:159], v[172:175], v[32:35]
	v_mfma_f32_16x16x32_bf16 v[20:23], v[148:151], v[180:183], v[20:23]
	v_mfma_f32_16x16x32_bf16 v[16:19], v[156:159], v[180:183], v[16:19]
	v_mfma_f32_16x16x32_bf16 v[4:7], v[148:151], v[208:211], v[4:7]
	v_mfma_f32_16x16x32_bf16 v[0:3], v[156:159], v[208:211], v[0:3]
	v_mfma_f32_16x16x32_bf16 v[52:55], v[152:155], v[168:171], v[52:55]
	v_mfma_f32_16x16x32_bf16 v[48:51], v[160:163], v[168:171], v[48:51]
	v_mfma_f32_16x16x32_bf16 v[36:39], v[152:155], v[176:179], v[36:39]
	v_mfma_f32_16x16x32_bf16 v[32:35], v[160:163], v[176:179], v[32:35]
	v_mfma_f32_16x16x32_bf16 v[20:23], v[152:155], v[204:207], v[20:23]
	v_mfma_f32_16x16x32_bf16 v[16:19], v[160:163], v[204:207], v[16:19]
	v_mfma_f32_16x16x32_bf16 v[4:7], v[152:155], v[212:215], v[4:7]
	v_mfma_f32_16x16x32_bf16 v[0:3], v[160:163], v[212:215], v[0:3]
	s_setprio 0
	s_barrier
	s_add_i32 s10, s71, 2
	s_add_u32 s38, s38, 0x100
	s_addc_u32 s39, s39, 0
	s_cmp_gt_u32 s71, 13
	s_mov_b32 s71, s10
	s_cbranch_scc1 .LBB0_1025
	s_branch .LBB0_1019
